# v31
# baseline (speedup 1.0000x reference)
; __device__ __forceinline__ void convert_matrix(const Ctx& C, const float* W, int K, int N, bf16* WT, int mode, const float* gs) {
;     ...
;     for (int it = gw; it < nitems; it += NGW) {
;         const int kb = it / nblk, nb = it % nblk, n0 = nb * 32;
;         int drow0 = n0;
;         if (mode == 1) { const int j = n0 < DFF ? n0 : n0 - DFF; drow0 = 256 * (j >> 7) + (j & 127) + (n0 < DFF ? 0 : 128); }
;         transpose_item(W, K, N, WT, kb * 64, n0, drow0, scr, C.lane, gs, mode);
.Lp0_loop:
	s_add_u32 s59, s58, s44
	s_cmp_lt_u32 s59, 41536
	s_cbranch_scc0 .Lp0_nonext
	s_mov_b32 s6, s59
	s_mov_b32 s7, 0
	s_cmp_lt_u32 s59, 26912
	s_cbranch_scc1 .Lp0_lay0_b
	s_sub_u32 s6, s59, 26912
	s_mov_b32 s7, 1

; __device__ __forceinline__ f32x4 mma16(bf16x8 x2, bf16x8 x1, f32x4 acc) { return __builtin_amdgcn_mfma_f32_16x16x32_bf16(x2, x1, acc, 0, 0, 0); }
; __device__ __forceinline__ void skinny_proj(const Ctx& C, const bf16* X, const bf16* Wt, const float* SS, bf16* PROJ) {
;     ...
;     for (int ks = 0; ks < D / 32; ++ks) {
;         const bf16x8 a = *(const bf16x8*)(A + ks * 32), b0 = *(const bf16x8*)(W0 + ks * 32), b1 = *(const bf16x8*)(W0 + (size_t)16 * D + ks * 32);
;         acc0 = mma16(b0, a, acc0); acc1 = mma16(b1, a, acc1);
;     }
.LBB0_323:
	v_lshl_add_u64 v[26:27], v[8:9], 0, s[6:7]
	v_add_co_u32_e32 v46, vcc, 0x1600000, v26
	v_lshl_add_u64 v[42:43], v[10:11], 0, s[6:7]
	s_nop 0
	v_addc_co_u32_e32 v47, vcc, 0, v27, vcc
	global_load_dwordx4 v[14:17], v[42:43], off offset:-256
	global_load_dwordx4 v[18:21], v[42:43], off offset:-192
	global_load_dwordx4 v[22:25], v[46:47], off
	v_add_co_u32_e32 v48, vcc, 0x1610000, v26
	s_add_u32 s6, s6, 0x200
	s_nop 0
	v_addc_co_u32_e32 v49, vcc, 0, v27, vcc
	global_load_dwordx4 v[26:29], v[46:47], off offset:64
	global_load_dwordx4 v[30:33], v[48:49], off
	s_addc_u32 s7, s7, 0
	s_cmpk_lg_i32 s6, 0x1000
	s_waitcnt vmcnt(0)
	v_mfma_f32_16x16x32_bf16 v[4:7], v[30:33], v[14:17], v[4:7]
	v_mfma_f32_16x16x32_bf16 v[0:3], v[22:25], v[14:17], v[0:3]
	global_load_dwordx4 v[22:25], v[48:49], off offset:64
	global_load_dwordx4 v[14:17], v[42:43], off offset:-128
	global_load_dwordx4 v[30:33], v[42:43], off offset:-64
	global_load_dwordx4 v[34:37], v[42:43], off
	v_mfma_f32_16x16x32_bf16 v[0:3], v[26:29], v[18:21], v[0:3]
	global_load_dwordx4 v[26:29], v[46:47], off offset:128
	global_load_dwordx4 v[38:41], v[46:47], off offset:192
	s_waitcnt vmcnt(1)
	v_mfma_f32_16x16x32_bf16 v[0:3], v[26:29], v[14:17], v[0:3]
	v_mfma_f32_16x16x32_bf16 v[4:7], v[22:25], v[18:21], v[4:7]
	global_load_dwordx4 v[18:21], v[48:49], off offset:128
	global_load_dwordx4 v[22:25], v[48:49], off offset:192
	s_waitcnt vmcnt(2)
	v_mfma_f32_16x16x32_bf16 v[0:3], v[38:41], v[30:33], v[0:3]
	s_waitcnt vmcnt(1)
	v_mfma_f32_16x16x32_bf16 v[4:7], v[18:21], v[14:17], v[4:7]
	global_load_dwordx4 v[14:17], v[42:43], off offset:64
	global_load_dwordx4 v[18:21], v[42:43], off offset:128
	global_load_dwordx4 v[26:29], v[42:43], off offset:192
	global_load_dwordx4 v[38:41], v[46:47], off offset:256
	s_nop 0
	global_load_dwordx4 v[42:45], v[46:47], off offset:320
	s_waitcnt vmcnt(5)
	v_mfma_f32_16x16x32_bf16 v[4:7], v[22:25], v[30:33], v[4:7]
	global_load_dwordx4 v[22:25], v[48:49], off offset:256
	global_load_dwordx4 v[30:33], v[48:49], off offset:320
	s_waitcnt vmcnt(3)
	v_mfma_f32_16x16x32_bf16 v[0:3], v[38:41], v[34:37], v[0:3]
	s_waitcnt vmcnt(1)
	v_mfma_f32_16x16x32_bf16 v[4:7], v[22:25], v[34:37], v[4:7]
	global_load_dwordx4 v[22:25], v[46:47], off offset:384
	global_load_dwordx4 v[34:37], v[48:49], off offset:384
	v_mfma_f32_16x16x32_bf16 v[0:3], v[42:45], v[14:17], v[0:3]
	s_waitcnt vmcnt(2)
	v_mfma_f32_16x16x32_bf16 v[4:7], v[30:33], v[14:17], v[4:7]
	global_load_dwordx4 v[14:17], v[46:47], off offset:448
	s_waitcnt vmcnt(2)
	v_mfma_f32_16x16x32_bf16 v[0:3], v[22:25], v[18:21], v[0:3]
	global_load_dwordx4 v[22:25], v[48:49], off offset:448
	s_waitcnt vmcnt(2)
	v_mfma_f32_16x16x32_bf16 v[4:7], v[34:37], v[18:21], v[4:7]
	s_waitcnt vmcnt(1)
	v_mfma_f32_16x16x32_bf16 v[0:3], v[14:17], v[26:29], v[0:3]
	s_waitcnt vmcnt(0)
	v_mfma_f32_16x16x32_bf16 v[4:7], v[22:25], v[26:29], v[4:7]
	s_cbranch_scc1 .LBB0_323
; #define LAS __attribute__((address_space(3)))
; __device__ __forceinline__ unsigned pk2(float lo, float hi) { return pg8::cvt_pk_bf16(lo, hi); }
; __device__ __forceinline__ void convert_matrix(const Ctx& C, const float* W, int K, int N, bf16* WT, int mode, const float* gs) {
;     LAS float* scr = (LAS float*)(C.lds + C.wave * 16384);
;     const int gw = C.bid * 8 + C.wave, NGW = C.G * 8;
;     const int nblk = N / 32, nitems = (K / 64) * nblk;
;     for (int it = gw; it < nitems; it += NGW) {
;         const int kb = it / nblk, nb = it % nblk, n0 = nb * 32;
;         int drow0 = n0;
;         if (mode == 1) { const int j = n0 < DFF ? n0 : n0 - DFF; drow0 = 256 * (j >> 7) + (j & 127) + (n0 < DFF ? 0 : 128); }
;         transpose_item(W, K, N, WT, kb * 64, n0, drow0, scr, C.lane, gs, mode);
; __device__ __forceinline__ void skinny_proj(const Ctx& C, const bf16* X, const bf16* Wt, const float* SS, bf16* PROJ) {
;     ...
;     const f32x4* p = (const f32x4*)(SS + (size_t)(r0 + fr) * 32); f32x4 sa = p[0];
; #pragma unroll
;     for (int q = 1; q < 8; ++q) sa = sa + p[q];
;     const float rs = rsqrtf(((sa[0] + sa[1]) + (sa[2] + sa[3])) * (1.0f / D) + EPS);
;     bf16* o = PROJ + (size_t)(r0 + fr) * LDP + NMAIN + 4 * fq;
;     *(v2u*)o = (v2u){pk2(acc0[0] * rs, acc0[1] * rs), pk2(acc0[2] * rs, acc0[3] * rs)};
;     *(v2u*)(o + 16) = (v2u){pk2(acc1[0] * rs, acc1[1] * rs), pk2(acc1[2] * rs, acc1[3] * rs)};
	s_addk_i32 s10, 0xc000
	v_or_b32_e32 v8, s10, v13
	v_add_u32_e32 v42, s11, v8
	v_ashrrev_i32_e32 v43, 31, v42
	v_lshlrev_b64 v[8:9], 7, v[42:43]
	v_lshl_add_u64 v[44:45], v[130:131], 0, v[8:9]
	global_load_dwordx4 v[8:11], v[44:45], off
	global_load_dwordx4 v[14:17], v[44:45], off offset:16
	global_load_dwordx4 v[18:21], v[44:45], off offset:32
	global_load_dwordx4 v[22:25], v[44:45], off offset:48
	global_load_dwordx4 v[26:29], v[44:45], off offset:64
	global_load_dwordx4 v[30:33], v[44:45], off offset:80
	global_load_dwordx4 v[34:37], v[44:45], off offset:96
	global_load_dwordx4 v[38:41], v[44:45], off offset:112
	v_and_b32_e32 v12, 3, v12
	s_movk_i32 s8, 0x2e00
	v_mov_b32_e32 v44, 0x358637bd
	v_mov_b32_e32 v13, 0
	v_lshlrev_b32_e32 v12, 3, v12
	v_mad_i64_i32 v[42:43], s[8:9], v42, s8, v[134:135]
	s_mov_b32 s10, 0x800000
	s_mov_b64 s[6:7], 0x2c00
	v_lshl_add_u64 v[12:13], v[42:43], 0, v[12:13]
	v_lshl_add_u64 v[42:43], v[12:13], 0, s[6:7]
	s_movk_i32 s11, 0x2000
	v_add_co_u32_e32 v12, vcc, s11, v12
	s_waitcnt vmcnt(6)
	v_pk_add_f32 v[10:11], v[10:11], v[16:17]
	v_pk_add_f32 v[8:9], v[8:9], v[14:15]
	s_waitcnt vmcnt(5)
	v_pk_add_f32 v[10:11], v[10:11], v[20:21]
	v_pk_add_f32 v[8:9], v[8:9], v[18:19]
	s_waitcnt vmcnt(4)
	v_pk_add_f32 v[10:11], v[10:11], v[24:25]
	v_pk_add_f32 v[8:9], v[8:9], v[22:23]
	s_waitcnt vmcnt(3)
	v_pk_add_f32 v[10:11], v[10:11], v[28:29]
	v_pk_add_f32 v[8:9], v[8:9], v[26:27]
	s_waitcnt vmcnt(2)
	v_pk_add_f32 v[10:11], v[10:11], v[32:33]
	v_pk_add_f32 v[8:9], v[8:9], v[30:31]
	s_waitcnt vmcnt(1)
	v_pk_add_f32 v[10:11], v[10:11], v[36:37]
	v_pk_add_f32 v[8:9], v[8:9], v[34:35]
	s_waitcnt vmcnt(0)
	v_pk_add_f32 v[10:11], v[10:11], v[40:41]
	v_pk_add_f32 v[8:9], v[8:9], v[38:39]
	v_addc_co_u32_e32 v13, vcc, 0, v13, vcc
	v_pk_mov_b32 v[14:15], v[8:9], v[10:11] op_sel:[1,0]
	v_mov_b32_e32 v9, v11
	v_pk_add_f32 v[8:9], v[14:15], v[8:9]
	s_nop 0
	v_add_f32_e32 v8, v8, v9
	v_fmac_f32_e32 v44, 0x3a000000, v8
	v_mul_f32_e32 v8, 0x4b800000, v44
	v_cmp_gt_f32_e64 s[6:7], s10, v44
	s_nop 1
	v_cndmask_b32_e64 v8, v44, v8, s[6:7]
	v_rsq_f32_e32 v8, v8
	s_nop 0
	v_mul_f32_e32 v9, 0x45800000, v8
	v_cndmask_b32_e64 v8, v8, v9, s[6:7]
	v_pk_mul_f32 v[0:1], v[0:1], v[8:9] op_sel_hi:[1,0]
	v_pk_mul_f32 v[2:3], v[2:3], v[8:9] op_sel_hi:[1,0]
	v_pk_mul_f32 v[4:5], v[4:5], v[8:9] op_sel_hi:[1,0]
	v_pk_mul_f32 v[6:7], v[6:7], v[8:9] op_sel_hi:[1,0]
	v_cvt_pk_bf16_f32 v0, v0, v1
	v_cvt_pk_bf16_f32 v1, v2, v3
	v_cvt_pk_bf16_f32 v2, v4, v5
	v_cvt_pk_bf16_f32 v3, v6, v7
	global_store_dwordx2 v[12:13], v[0:1], off offset:3072
	global_store_dwordx2 v[42:43], v[2:3], off offset:32
	v_writelane_b32 v250, s6, 0
	v_writelane_b32 v250, s7, 1
	v_writelane_b32 v250, s8, 2
	v_writelane_b32 v250, s9, 3
	v_writelane_b32 v250, s10, 4
	v_writelane_b32 v250, s11, 5
	v_writelane_b32 v250, s12, 6
	v_writelane_b32 v250, s13, 7
	v_writelane_b32 v250, s14, 8
	v_writelane_b32 v250, s15, 9
	v_writelane_b32 v250, s16, 10
	v_writelane_b32 v250, s17, 11
	v_writelane_b32 v250, s18, 12
	v_writelane_b32 v250, s19, 13
	v_writelane_b32 v250, s20, 14
	v_writelane_b32 v250, s21, 15
	v_writelane_b32 v250, s22, 16
	v_writelane_b32 v250, s23, 17
	v_writelane_b32 v250, s24, 18
	v_writelane_b32 v250, s25, 19
	v_writelane_b32 v250, s26, 20
	v_writelane_b32 v250, s27, 21
	v_writelane_b32 v250, s28, 22
	v_writelane_b32 v250, s29, 23
	v_writelane_b32 v250, s30, 24
	v_writelane_b32 v250, s31, 25
	v_writelane_b32 v250, s32, 26
	v_writelane_b32 v250, s33, 27
	v_writelane_b32 v250, s34, 28
	v_writelane_b32 v250, s35, 29
	v_writelane_b32 v250, s36, 30
	v_writelane_b32 v250, s37, 31
	v_writelane_b32 v250, s38, 32
	v_writelane_b32 v250, s39, 33
	v_writelane_b32 v250, s40, 34
	v_writelane_b32 v250, s41, 35
	v_writelane_b32 v250, s42, 36
	v_writelane_b32 v250, s43, 37
	v_writelane_b32 v250, s44, 38
	v_writelane_b32 v250, s45, 39
	v_writelane_b32 v250, s46, 40
	v_writelane_b32 v250, s47, 41
	v_writelane_b32 v250, s48, 42
	v_writelane_b32 v250, s49, 43
	v_writelane_b32 v250, s50, 44
	v_writelane_b32 v250, s51, 45
	v_writelane_b32 v250, s52, 46
	v_writelane_b32 v250, s53, 47
	v_writelane_b32 v250, s54, 48
	v_writelane_b32 v250, s55, 49
	v_writelane_b32 v250, s56, 50
	v_writelane_b32 v250, s57, 51
	v_writelane_b32 v250, s58, 52
	v_writelane_b32 v250, s59, 53
	v_writelane_b32 v250, s60, 54
	v_writelane_b32 v250, s61, 55
	v_writelane_b32 v250, s62, 56
	v_writelane_b32 v250, s63, 57
	v_writelane_b32 v250, s64, 58
	v_writelane_b32 v250, s65, 59
	v_writelane_b32 v250, s66, 60
	v_writelane_b32 v250, s67, 61
	v_writelane_b32 v250, s68, 62
	v_writelane_b32 v250, s69, 63
	v_writelane_b32 v251, s70, 0
	v_writelane_b32 v251, s71, 1
	v_writelane_b32 v251, s72, 2
	v_writelane_b32 v251, s73, 3
	v_writelane_b32 v251, s74, 4
	v_writelane_b32 v251, s75, 5
	v_writelane_b32 v251, s76, 6
	v_writelane_b32 v251, s77, 7
	v_writelane_b32 v251, s78, 8
	v_writelane_b32 v251, s79, 9
	s_load_dwordx4 s[24:27], s[0:1], 0x10
	s_load_dwordx2 s[28:29], s[0:1], 0x68
	s_load_dwordx4 s[36:39], s[0:1], 0x70
	s_load_dwordx2 s[30:31], s[0:1], 0x90
	s_load_dwordx4 s[40:43], s[0:1], 0x98
	s_load_dwordx2 s[34:35], s[0:1], 0xa8
	s_load_dwordx2 s[48:49], s[0:1], 0xc0
	s_load_dwordx4 s[64:67], s[0:1], 0x0
	v_readfirstlane_b32 s78, v234
	s_lshr_b32 s78, s78, 6
	s_sub_u32 s58, s2, 128
	s_lshl_b32 s58, s58, 3
	s_add_u32 s58, s58, s78
	s_add_u32 s58, s58, 41536
	s_lshl_b32 s78, s78, 14
	v_and_b32_e32 v1, 63, v234
	v_lshrrev_b32_e32 v6, 5, v1
	v_and_b32_e32 v7, 31, v1
	v_lshlrev_b32_e32 v7, 2, v7
	v_mul_u32_u24_e32 v2, 0x84, v6
	v_add3_u32 v2, s78, v2, v7
	v_and_b32_e32 v4, 7, v1
	v_lshrrev_b32_e32 v8, 3, v1
	v_mul_u32_u24_e32 v3, 0x420, v4
	v_lshlrev_b32_e32 v108, 2, v8
	v_add3_u32 v3, s78, v3, v108
	v_lshlrev_b32_e32 v5, 5, v4
	v_lshlrev_b32_e32 v4, 4, v4
	v_mov_b32_e32 v10, 0
	s_waitcnt lgkmcnt(0)
	s_mov_b32 s6, s58
	s_mov_b32 s7, 0
	s_cmp_lt_u32 s58, 26912
	s_cbranch_scc1 .Lq0_lay0_a
	s_sub_u32 s6, s58, 26912
	s_mov_b32 s7, 1

; __device__ __forceinline__ void final_norm_pass(const Ctx& C, const bf16* XB, const float* g, float* out) {
;     ...
;     for (int m = gw; m < M; m += NGW) {
;         const v2u* xr = (const v2u*)(XB + (size_t)m * D) + C.lane; f32x4 v[8]; float s = 0.f;
; #pragma unroll
;         for (int j = 0; j < 8; ++j) { const v2u w = xr[64 * j]; v[j] = (f32x4){__uint_as_float(w.x << 16), __uint_as_float(w.x & 0xffff0000u), __uint_as_float(w.y << 16), __uint_as_float(w.y & 0xffff0000u)};
;             s += (v[j][0] * v[j][0] + v[j][1] * v[j][1]) + (v[j][2] * v[j][2] + v[j][3] * v[j][3]); }
;         const float rstd = rsqrtf(wave_sum(s) * (1.0f / D) + EPS);
.LBB0_2444:
	s_or_b64 exec, exec, s[2:3]
	s_waitcnt lgkmcnt(0)
	s_barrier
	v_readlane_b32 s3, v254, 0
	v_readfirstlane_b32 s2, v234
	s_ashr_i32 s2, s2, 6
	s_add_i32 s2, s2, s3
	s_mov_b32 s8, 0
	s_cmpk_gt_i32 s2, 0x3fff
	s_cbranch_scc1 .LBB0_2447
	s_load_dwordx2 s[12:13], s[0:1], 0xb0
	s_load_dwordx4 s[4:7], s[0:1], 0xb8
	v_and_b32_e32 v1, 63, v234
	v_lshlrev_b32_e32 v2, 4, v1
	v_lshlrev_b32_e32 v3, 3, v1
	v_lshlrev_b32_e32 v4, 2, v1
	v_xor_b32_e32 v10, 4, v4
	v_xor_b32_e32 v11, 8, v4
	v_xor_b32_e32 v12, 16, v4
	v_xor_b32_e32 v13, 32, v4
	v_xor_b32_e32 v14, 64, v4
	v_xor_b32_e32 v15, 128, v4
	v_mov_b32_e32 v5, 0x358637bd
	s_waitcnt lgkmcnt(0)
	s_add_u32 s12, s12, 0x1000
	s_addc_u32 s13, s13, 0
	global_load_dwordx4 v[128:131], v2, s[12:13] offset:-4096
	global_load_dwordx4 v[132:135], v2, s[12:13] offset:-3072
	global_load_dwordx4 v[136:139], v2, s[12:13] offset:-2048
	global_load_dwordx4 v[140:143], v2, s[12:13] offset:-1024
	global_load_dwordx4 v[144:147], v2, s[12:13] offset:0
	global_load_dwordx4 v[148:151], v2, s[12:13] offset:1024
	global_load_dwordx4 v[152:155], v2, s[12:13] offset:2048
	global_load_dwordx4 v[156:159], v2, s[12:13] offset:3072
	s_add_u32 s6, s6, 0x26100800
	s_addc_u32 s7, s7, 0
	s_add_u32 s4, s4, 0x1000
	s_addc_u32 s5, s5, 0
	s_lshl_b32 s8, s2, 12
	s_add_u32 s10, s6, s8
	s_addc_u32 s11, s7, 0
	global_load_dwordx2 v[20:21], v3, s[10:11] offset:-2048
	global_load_dwordx2 v[22:23], v3, s[10:11] offset:-1536
	global_load_dwordx2 v[24:25], v3, s[10:11] offset:-1024
	global_load_dwordx2 v[26:27], v3, s[10:11] offset:-512
	global_load_dwordx2 v[28:29], v3, s[10:11] offset:0
	global_load_dwordx2 v[30:31], v3, s[10:11] offset:512
	global_load_dwordx2 v[32:33], v3, s[10:11] offset:1024
	global_load_dwordx2 v[34:35], v3, s[10:11] offset:1536
	s_lshl_b32 s8, s2, 13
	s_add_u32 s14, s4, s8
	s_addc_u32 s15, s5, 0
	s_add_u32 s2, s2, s44
	s_lshl_b32 s8, s2, 12
	s_add_u32 s10, s6, s8
	s_addc_u32 s11, s7, 0
	global_load_dwordx2 v[36:37], v3, s[10:11] offset:-2048
	global_load_dwordx2 v[38:39], v3, s[10:11] offset:-1536
	global_load_dwordx2 v[40:41], v3, s[10:11] offset:-1024
	global_load_dwordx2 v[42:43], v3, s[10:11] offset:-512
	global_load_dwordx2 v[44:45], v3, s[10:11] offset:0
	global_load_dwordx2 v[46:47], v3, s[10:11] offset:512
	global_load_dwordx2 v[48:49], v3, s[10:11] offset:1024
	global_load_dwordx2 v[50:51], v3, s[10:11] offset:1536
	s_waitcnt vmcnt(8)
	v_lshlrev_b32_e32 v64, 16, v20
	v_and_b32_e32 v65, 0xffff0000, v20
	v_lshlrev_b32_e32 v66, 16, v21
	v_and_b32_e32 v67, 0xffff0000, v21
	v_mul_f32_e32 v8, v65, v65
	v_mul_f32_e32 v9, v67, v67
	v_fmac_f32_e32 v8, v64, v64
	v_fmac_f32_e32 v9, v66, v66
	v_add_f32_e32 v17, v8, v9
	v_lshlrev_b32_e32 v68, 16, v22
	v_and_b32_e32 v69, 0xffff0000, v22
	v_lshlrev_b32_e32 v70, 16, v23
	v_and_b32_e32 v71, 0xffff0000, v23
	v_mul_f32_e32 v8, v69, v69
	v_mul_f32_e32 v9, v71, v71
	v_fmac_f32_e32 v8, v68, v68
	v_fmac_f32_e32 v9, v70, v70
	v_add_f32_e32 v8, v8, v9
	v_add_f32_e32 v17, v17, v8
	v_lshlrev_b32_e32 v72, 16, v24
	v_and_b32_e32 v73, 0xffff0000, v24
	v_lshlrev_b32_e32 v74, 16, v25
	v_and_b32_e32 v75, 0xffff0000, v25
	v_mul_f32_e32 v8, v73, v73
	v_mul_f32_e32 v9, v75, v75
	v_fmac_f32_e32 v8, v72, v72
	v_fmac_f32_e32 v9, v74, v74
	v_add_f32_e32 v8, v8, v9
	v_add_f32_e32 v17, v17, v8
	v_lshlrev_b32_e32 v76, 16, v26
	v_and_b32_e32 v77, 0xffff0000, v26
	v_lshlrev_b32_e32 v78, 16, v27
	v_and_b32_e32 v79, 0xffff0000, v27
	v_mul_f32_e32 v8, v77, v77
	v_mul_f32_e32 v9, v79, v79
	v_fmac_f32_e32 v8, v76, v76
	v_fmac_f32_e32 v9, v78, v78
	v_add_f32_e32 v8, v8, v9
	v_add_f32_e32 v17, v17, v8
	v_lshlrev_b32_e32 v80, 16, v28
	v_and_b32_e32 v81, 0xffff0000, v28
	v_lshlrev_b32_e32 v82, 16, v29
	v_and_b32_e32 v83, 0xffff0000, v29
	v_mul_f32_e32 v8, v81, v81
	v_mul_f32_e32 v9, v83, v83
	v_fmac_f32_e32 v8, v80, v80
	v_fmac_f32_e32 v9, v82, v82
	v_add_f32_e32 v8, v8, v9
	v_add_f32_e32 v17, v17, v8
	v_lshlrev_b32_e32 v84, 16, v30
	v_and_b32_e32 v85, 0xffff0000, v30
	v_lshlrev_b32_e32 v86, 16, v31
	v_and_b32_e32 v87, 0xffff0000, v31
	v_mul_f32_e32 v8, v85, v85
	v_mul_f32_e32 v9, v87, v87
	v_fmac_f32_e32 v8, v84, v84
	v_fmac_f32_e32 v9, v86, v86
	v_add_f32_e32 v8, v8, v9
	v_add_f32_e32 v17, v17, v8
	v_lshlrev_b32_e32 v88, 16, v32
	v_and_b32_e32 v89, 0xffff0000, v32
	v_lshlrev_b32_e32 v90, 16, v33
	v_and_b32_e32 v91, 0xffff0000, v33
	v_mul_f32_e32 v8, v89, v89
	v_mul_f32_e32 v9, v91, v91
	v_fmac_f32_e32 v8, v88, v88
	v_fmac_f32_e32 v9, v90, v90
	v_add_f32_e32 v8, v8, v9
	v_add_f32_e32 v17, v17, v8
	v_lshlrev_b32_e32 v92, 16, v34
	v_and_b32_e32 v93, 0xffff0000, v34
	v_lshlrev_b32_e32 v94, 16, v35
	v_and_b32_e32 v95, 0xffff0000, v35
	v_mul_f32_e32 v8, v93, v93
	v_mul_f32_e32 v9, v95, v95
	v_fmac_f32_e32 v8, v92, v92
	v_fmac_f32_e32 v9, v94, v94
	v_add_f32_e32 v8, v8, v9
	v_add_f32_e32 v17, v17, v8
	ds_bpermute_b32 v18, v10, v17
	s_waitcnt lgkmcnt(0)
	v_add_f32_e32 v17, v17, v18
	ds_bpermute_b32 v18, v11, v17
	s_waitcnt lgkmcnt(0)
	v_add_f32_e32 v17, v17, v18
	ds_bpermute_b32 v18, v12, v17
	s_waitcnt lgkmcnt(0)
	v_add_f32_e32 v17, v17, v18
	ds_bpermute_b32 v18, v13, v17
	s_waitcnt lgkmcnt(0)
	v_add_f32_e32 v17, v17, v18
	ds_bpermute_b32 v18, v14, v17
	s_waitcnt lgkmcnt(0)
	v_add_f32_e32 v17, v17, v18
	ds_bpermute_b32 v18, v15, v17
	s_waitcnt lgkmcnt(0)
; __device__ __forceinline__ void final_norm_pass(const Ctx& C, const bf16* XB, const float* g, float* out) {
;     ...
;         const v2u* xr = (const v2u*)(XB + (size_t)m * D) + C.lane; f32x4 v[8]; float s = 0.f;
; #pragma unroll
;         for (int j = 0; j < 8; ++j) { const v2u w = xr[64 * j]; v[j] = (f32x4){__uint_as_float(w.x << 16), __uint_as_float(w.x & 0xffff0000u), __uint_as_float(w.y << 16), __uint_as_float(w.y & 0xffff0000u)};
;             s += (v[j][0] * v[j][0] + v[j][1] * v[j][1]) + (v[j][2] * v[j][2] + v[j][3] * v[j][3]); }
;         const float rstd = rsqrtf(wave_sum(s) * (1.0f / D) + EPS);
;         const f32x4* gr = (const f32x4*)g + C.lane; f32x4* o = (f32x4*)(out + (size_t)m * D) + C.lane;
; #pragma unroll
;         for (int j = 0; j < 8; ++j) o[64 * j] = v[j] * rstd * gr[64 * j];
	v_add_f32_e32 v17, v17, v18
	v_fmamk_f32 v6, v17, 0x3a000000, v5
	v_rsq_f32_e32 v6, v6
	s_nop 0
	v_pk_mul_f32 v[64:65], v[6:7], v[64:65] op_sel_hi:[0,1]
	v_pk_mul_f32 v[66:67], v[6:7], v[66:67] op_sel_hi:[0,1]
	v_pk_mul_f32 v[96:97], v[128:129], v[64:65]
	v_pk_mul_f32 v[98:99], v[130:131], v[66:67]
	global_store_dwordx4 v2, v[96:99], s[14:15] offset:-4096 sc0 sc1
	v_pk_mul_f32 v[68:69], v[6:7], v[68:69] op_sel_hi:[0,1]
	v_pk_mul_f32 v[70:71], v[6:7], v[70:71] op_sel_hi:[0,1]
	v_pk_mul_f32 v[100:101], v[132:133], v[68:69]
	v_pk_mul_f32 v[102:103], v[134:135], v[70:71]
	global_store_dwordx4 v2, v[100:103], s[14:15] offset:-3072 sc0 sc1
	v_pk_mul_f32 v[72:73], v[6:7], v[72:73] op_sel_hi:[0,1]
	v_pk_mul_f32 v[74:75], v[6:7], v[74:75] op_sel_hi:[0,1]
	v_pk_mul_f32 v[104:105], v[136:137], v[72:73]
	v_pk_mul_f32 v[106:107], v[138:139], v[74:75]
	global_store_dwordx4 v2, v[104:107], s[14:15] offset:-2048 sc0 sc1
	v_pk_mul_f32 v[76:77], v[6:7], v[76:77] op_sel_hi:[0,1]
	v_pk_mul_f32 v[78:79], v[6:7], v[78:79] op_sel_hi:[0,1]
	v_pk_mul_f32 v[108:109], v[140:141], v[76:77]
	v_pk_mul_f32 v[110:111], v[142:143], v[78:79]
	global_store_dwordx4 v2, v[108:111], s[14:15] offset:-1024 sc0 sc1
	v_pk_mul_f32 v[80:81], v[6:7], v[80:81] op_sel_hi:[0,1]
	v_pk_mul_f32 v[82:83], v[6:7], v[82:83] op_sel_hi:[0,1]
	v_pk_mul_f32 v[112:113], v[144:145], v[80:81]
	v_pk_mul_f32 v[114:115], v[146:147], v[82:83]
	global_store_dwordx4 v2, v[112:115], s[14:15] offset:0 sc0 sc1
	v_pk_mul_f32 v[84:85], v[6:7], v[84:85] op_sel_hi:[0,1]
	v_pk_mul_f32 v[86:87], v[6:7], v[86:87] op_sel_hi:[0,1]
	v_pk_mul_f32 v[116:117], v[148:149], v[84:85]
	v_pk_mul_f32 v[118:119], v[150:151], v[86:87]
	global_store_dwordx4 v2, v[116:119], s[14:15] offset:1024 sc0 sc1
	v_pk_mul_f32 v[88:89], v[6:7], v[88:89] op_sel_hi:[0,1]
	v_pk_mul_f32 v[90:91], v[6:7], v[90:91] op_sel_hi:[0,1]
	v_pk_mul_f32 v[120:121], v[152:153], v[88:89]
	v_pk_mul_f32 v[122:123], v[154:155], v[90:91]
	global_store_dwordx4 v2, v[120:123], s[14:15] offset:2048 sc0 sc1
	v_pk_mul_f32 v[92:93], v[6:7], v[92:93] op_sel_hi:[0,1]
	v_pk_mul_f32 v[94:95], v[6:7], v[94:95] op_sel_hi:[0,1]
	v_pk_mul_f32 v[124:125], v[156:157], v[92:93]
	v_pk_mul_f32 v[126:127], v[158:159], v[94:95]
	global_store_dwordx4 v2, v[124:127], s[14:15] offset:3072 sc0 sc1
	s_lshl_b32 s8, s2, 13
	s_add_u32 s14, s4, s8
	s_addc_u32 s15, s5, 0
	s_add_u32 s2, s2, s44
	s_lshl_b32 s8, s2, 12
	s_add_u32 s10, s6, s8
	s_addc_u32 s11, s7, 0
	global_load_dwordx2 v[20:21], v3, s[10:11] offset:-2048
	global_load_dwordx2 v[22:23], v3, s[10:11] offset:-1536
	global_load_dwordx2 v[24:25], v3, s[10:11] offset:-1024
	global_load_dwordx2 v[26:27], v3, s[10:11] offset:-512
	global_load_dwordx2 v[28:29], v3, s[10:11] offset:0
	global_load_dwordx2 v[30:31], v3, s[10:11] offset:512
	global_load_dwordx2 v[32:33], v3, s[10:11] offset:1024
	global_load_dwordx2 v[34:35], v3, s[10:11] offset:1536
	s_waitcnt vmcnt(16)
	v_lshlrev_b32_e32 v64, 16, v36
	v_and_b32_e32 v65, 0xffff0000, v36
	v_lshlrev_b32_e32 v66, 16, v37
	v_and_b32_e32 v67, 0xffff0000, v37
	v_mul_f32_e32 v8, v65, v65
	v_mul_f32_e32 v9, v67, v67
	v_fmac_f32_e32 v8, v64, v64
	v_fmac_f32_e32 v9, v66, v66
	v_add_f32_e32 v17, v8, v9
	v_lshlrev_b32_e32 v68, 16, v38
	v_and_b32_e32 v69, 0xffff0000, v38
	v_lshlrev_b32_e32 v70, 16, v39
	v_and_b32_e32 v71, 0xffff0000, v39
	v_mul_f32_e32 v8, v69, v69
	v_mul_f32_e32 v9, v71, v71
	v_fmac_f32_e32 v8, v68, v68
	v_fmac_f32_e32 v9, v70, v70
	v_add_f32_e32 v8, v8, v9
	v_add_f32_e32 v17, v17, v8
	v_lshlrev_b32_e32 v72, 16, v40
	v_and_b32_e32 v73, 0xffff0000, v40
	v_lshlrev_b32_e32 v74, 16, v41
	v_and_b32_e32 v75, 0xffff0000, v41
	v_mul_f32_e32 v8, v73, v73
	v_mul_f32_e32 v9, v75, v75
	v_fmac_f32_e32 v8, v72, v72
	v_fmac_f32_e32 v9, v74, v74
	v_add_f32_e32 v8, v8, v9
	v_add_f32_e32 v17, v17, v8
	v_lshlrev_b32_e32 v76, 16, v42
	v_and_b32_e32 v77, 0xffff0000, v42
	v_lshlrev_b32_e32 v78, 16, v43
	v_and_b32_e32 v79, 0xffff0000, v43
	v_mul_f32_e32 v8, v77, v77
	v_mul_f32_e32 v9, v79, v79
	v_fmac_f32_e32 v8, v76, v76
	v_fmac_f32_e32 v9, v78, v78
	v_add_f32_e32 v8, v8, v9
	v_add_f32_e32 v17, v17, v8
	v_lshlrev_b32_e32 v80, 16, v44
	v_and_b32_e32 v81, 0xffff0000, v44
	v_lshlrev_b32_e32 v82, 16, v45
	v_and_b32_e32 v83, 0xffff0000, v45
	v_mul_f32_e32 v8, v81, v81
	v_mul_f32_e32 v9, v83, v83
	v_fmac_f32_e32 v8, v80, v80
	v_fmac_f32_e32 v9, v82, v82
	v_add_f32_e32 v8, v8, v9
	v_add_f32_e32 v17, v17, v8
	v_lshlrev_b32_e32 v84, 16, v46
	v_and_b32_e32 v85, 0xffff0000, v46
	v_lshlrev_b32_e32 v86, 16, v47
	v_and_b32_e32 v87, 0xffff0000, v47
	v_mul_f32_e32 v8, v85, v85
	v_mul_f32_e32 v9, v87, v87
	v_fmac_f32_e32 v8, v84, v84
	v_fmac_f32_e32 v9, v86, v86
	v_add_f32_e32 v8, v8, v9
	v_add_f32_e32 v17, v17, v8
	v_lshlrev_b32_e32 v88, 16, v48
	v_and_b32_e32 v89, 0xffff0000, v48
	v_lshlrev_b32_e32 v90, 16, v49
	v_and_b32_e32 v91, 0xffff0000, v49
	v_mul_f32_e32 v8, v89, v89
	v_mul_f32_e32 v9, v91, v91
	v_fmac_f32_e32 v8, v88, v88
	v_fmac_f32_e32 v9, v90, v90
	v_add_f32_e32 v8, v8, v9
	v_add_f32_e32 v17, v17, v8
	v_lshlrev_b32_e32 v92, 16, v50
	v_and_b32_e32 v93, 0xffff0000, v50
	v_lshlrev_b32_e32 v94, 16, v51
	v_and_b32_e32 v95, 0xffff0000, v51
	v_mul_f32_e32 v8, v93, v93
	v_mul_f32_e32 v9, v95, v95
	v_fmac_f32_e32 v8, v92, v92
	v_fmac_f32_e32 v9, v94, v94
	v_add_f32_e32 v8, v8, v9
	v_add_f32_e32 v17, v17, v8
	ds_bpermute_b32 v18, v10, v17
	s_waitcnt lgkmcnt(0)
	v_add_f32_e32 v17, v17, v18
	ds_bpermute_b32 v18, v11, v17
	s_waitcnt lgkmcnt(0)
	v_add_f32_e32 v17, v17, v18
	ds_bpermute_b32 v18, v12, v17
	s_waitcnt lgkmcnt(0)
	v_add_f32_e32 v17, v17, v18
	ds_bpermute_b32 v18, v13, v17
	s_waitcnt lgkmcnt(0)
; __device__ __forceinline__ void final_norm_pass(const Ctx& C, const bf16* XB, const float* g, float* out) {
;     ...
;         const v2u* xr = (const v2u*)(XB + (size_t)m * D) + C.lane; f32x4 v[8]; float s = 0.f;
; #pragma unroll
;         for (int j = 0; j < 8; ++j) { const v2u w = xr[64 * j]; v[j] = (f32x4){__uint_as_float(w.x << 16), __uint_as_float(w.x & 0xffff0000u), __uint_as_float(w.y << 16), __uint_as_float(w.y & 0xffff0000u)};
;             s += (v[j][0] * v[j][0] + v[j][1] * v[j][1]) + (v[j][2] * v[j][2] + v[j][3] * v[j][3]); }
;         const float rstd = rsqrtf(wave_sum(s) * (1.0f / D) + EPS);
;         const f32x4* gr = (const f32x4*)g + C.lane; f32x4* o = (f32x4*)(out + (size_t)m * D) + C.lane;
; #pragma unroll
;         for (int j = 0; j < 8; ++j) o[64 * j] = v[j] * rstd * gr[64 * j];
	v_add_f32_e32 v17, v17, v18
	ds_bpermute_b32 v18, v14, v17
	s_waitcnt lgkmcnt(0)
	v_add_f32_e32 v17, v17, v18
	ds_bpermute_b32 v18, v15, v17
	s_waitcnt lgkmcnt(0)
	v_add_f32_e32 v17, v17, v18
	v_fmamk_f32 v6, v17, 0x3a000000, v5
	v_rsq_f32_e32 v6, v6
	s_nop 0
	v_pk_mul_f32 v[64:65], v[6:7], v[64:65] op_sel_hi:[0,1]
	v_pk_mul_f32 v[66:67], v[6:7], v[66:67] op_sel_hi:[0,1]
	v_pk_mul_f32 v[96:97], v[128:129], v[64:65]
	v_pk_mul_f32 v[98:99], v[130:131], v[66:67]
	global_store_dwordx4 v2, v[96:99], s[14:15] offset:-4096 sc0 sc1
	v_pk_mul_f32 v[68:69], v[6:7], v[68:69] op_sel_hi:[0,1]
	v_pk_mul_f32 v[70:71], v[6:7], v[70:71] op_sel_hi:[0,1]
	v_pk_mul_f32 v[100:101], v[132:133], v[68:69]
	v_pk_mul_f32 v[102:103], v[134:135], v[70:71]
	global_store_dwordx4 v2, v[100:103], s[14:15] offset:-3072 sc0 sc1
	v_pk_mul_f32 v[72:73], v[6:7], v[72:73] op_sel_hi:[0,1]
	v_pk_mul_f32 v[74:75], v[6:7], v[74:75] op_sel_hi:[0,1]
	v_pk_mul_f32 v[104:105], v[136:137], v[72:73]
	v_pk_mul_f32 v[106:107], v[138:139], v[74:75]
	global_store_dwordx4 v2, v[104:107], s[14:15] offset:-2048 sc0 sc1
	v_pk_mul_f32 v[76:77], v[6:7], v[76:77] op_sel_hi:[0,1]
	v_pk_mul_f32 v[78:79], v[6:7], v[78:79] op_sel_hi:[0,1]
	v_pk_mul_f32 v[108:109], v[140:141], v[76:77]
	v_pk_mul_f32 v[110:111], v[142:143], v[78:79]
	global_store_dwordx4 v2, v[108:111], s[14:15] offset:-1024 sc0 sc1
	v_pk_mul_f32 v[80:81], v[6:7], v[80:81] op_sel_hi:[0,1]
	v_pk_mul_f32 v[82:83], v[6:7], v[82:83] op_sel_hi:[0,1]
	v_pk_mul_f32 v[112:113], v[144:145], v[80:81]
	v_pk_mul_f32 v[114:115], v[146:147], v[82:83]
	global_store_dwordx4 v2, v[112:115], s[14:15] offset:0 sc0 sc1
	v_pk_mul_f32 v[84:85], v[6:7], v[84:85] op_sel_hi:[0,1]
	v_pk_mul_f32 v[86:87], v[6:7], v[86:87] op_sel_hi:[0,1]
	v_pk_mul_f32 v[116:117], v[148:149], v[84:85]
	v_pk_mul_f32 v[118:119], v[150:151], v[86:87]
	global_store_dwordx4 v2, v[116:119], s[14:15] offset:1024 sc0 sc1
	v_pk_mul_f32 v[88:89], v[6:7], v[88:89] op_sel_hi:[0,1]
	v_pk_mul_f32 v[90:91], v[6:7], v[90:91] op_sel_hi:[0,1]
	v_pk_mul_f32 v[120:121], v[152:153], v[88:89]
	v_pk_mul_f32 v[122:123], v[154:155], v[90:91]
	global_store_dwordx4 v2, v[120:123], s[14:15] offset:2048 sc0 sc1
	v_pk_mul_f32 v[92:93], v[6:7], v[92:93] op_sel_hi:[0,1]
	v_pk_mul_f32 v[94:95], v[6:7], v[94:95] op_sel_hi:[0,1]
	v_pk_mul_f32 v[124:125], v[156:157], v[92:93]
	v_pk_mul_f32 v[126:127], v[158:159], v[94:95]
	global_store_dwordx4 v2, v[124:127], s[14:15] offset:3072 sc0 sc1
	s_lshl_b32 s8, s2, 13
	s_add_u32 s14, s4, s8
	s_addc_u32 s15, s5, 0
	s_add_u32 s2, s2, s44
	s_lshl_b32 s8, s2, 12
	s_add_u32 s10, s6, s8
	s_addc_u32 s11, s7, 0
	global_load_dwordx2 v[36:37], v3, s[10:11] offset:-2048
	global_load_dwordx2 v[38:39], v3, s[10:11] offset:-1536
	global_load_dwordx2 v[40:41], v3, s[10:11] offset:-1024
	global_load_dwordx2 v[42:43], v3, s[10:11] offset:-512
	global_load_dwordx2 v[44:45], v3, s[10:11] offset:0
	global_load_dwordx2 v[46:47], v3, s[10:11] offset:512
	global_load_dwordx2 v[48:49], v3, s[10:11] offset:1024
	global_load_dwordx2 v[50:51], v3, s[10:11] offset:1536
	s_waitcnt vmcnt(16)
	v_lshlrev_b32_e32 v64, 16, v20
	v_and_b32_e32 v65, 0xffff0000, v20
	v_lshlrev_b32_e32 v66, 16, v21
	v_and_b32_e32 v67, 0xffff0000, v21
	v_mul_f32_e32 v8, v65, v65
	v_mul_f32_e32 v9, v67, v67
	v_fmac_f32_e32 v8, v64, v64
	v_fmac_f32_e32 v9, v66, v66
	v_add_f32_e32 v17, v8, v9
	v_lshlrev_b32_e32 v68, 16, v22
	v_and_b32_e32 v69, 0xffff0000, v22
	v_lshlrev_b32_e32 v70, 16, v23
	v_and_b32_e32 v71, 0xffff0000, v23
	v_mul_f32_e32 v8, v69, v69
	v_mul_f32_e32 v9, v71, v71
	v_fmac_f32_e32 v8, v68, v68
	v_fmac_f32_e32 v9, v70, v70
	v_add_f32_e32 v8, v8, v9
	v_add_f32_e32 v17, v17, v8
	v_lshlrev_b32_e32 v72, 16, v24
	v_and_b32_e32 v73, 0xffff0000, v24
	v_lshlrev_b32_e32 v74, 16, v25
	v_and_b32_e32 v75, 0xffff0000, v25
	v_mul_f32_e32 v8, v73, v73
	v_mul_f32_e32 v9, v75, v75
	v_fmac_f32_e32 v8, v72, v72
	v_fmac_f32_e32 v9, v74, v74
	v_add_f32_e32 v8, v8, v9
	v_add_f32_e32 v17, v17, v8
	v_lshlrev_b32_e32 v76, 16, v26
	v_and_b32_e32 v77, 0xffff0000, v26
	v_lshlrev_b32_e32 v78, 16, v27
	v_and_b32_e32 v79, 0xffff0000, v27
	v_mul_f32_e32 v8, v77, v77
	v_mul_f32_e32 v9, v79, v79
	v_fmac_f32_e32 v8, v76, v76
	v_fmac_f32_e32 v9, v78, v78
	v_add_f32_e32 v8, v8, v9
	v_add_f32_e32 v17, v17, v8
	v_lshlrev_b32_e32 v80, 16, v28
	v_and_b32_e32 v81, 0xffff0000, v28
	v_lshlrev_b32_e32 v82, 16, v29
	v_and_b32_e32 v83, 0xffff0000, v29
	v_mul_f32_e32 v8, v81, v81
	v_mul_f32_e32 v9, v83, v83
	v_fmac_f32_e32 v8, v80, v80
	v_fmac_f32_e32 v9, v82, v82
	v_add_f32_e32 v8, v8, v9
	v_add_f32_e32 v17, v17, v8
	v_lshlrev_b32_e32 v84, 16, v30
	v_and_b32_e32 v85, 0xffff0000, v30
	v_lshlrev_b32_e32 v86, 16, v31
	v_and_b32_e32 v87, 0xffff0000, v31
	v_mul_f32_e32 v8, v85, v85
	v_mul_f32_e32 v9, v87, v87
	v_fmac_f32_e32 v8, v84, v84
	v_fmac_f32_e32 v9, v86, v86
	v_add_f32_e32 v8, v8, v9
	v_add_f32_e32 v17, v17, v8
	v_lshlrev_b32_e32 v88, 16, v32
	v_and_b32_e32 v89, 0xffff0000, v32
	v_lshlrev_b32_e32 v90, 16, v33
	v_and_b32_e32 v91, 0xffff0000, v33
	v_mul_f32_e32 v8, v89, v89
	v_mul_f32_e32 v9, v91, v91
	v_fmac_f32_e32 v8, v88, v88
	v_fmac_f32_e32 v9, v90, v90
	v_add_f32_e32 v8, v8, v9
	v_add_f32_e32 v17, v17, v8
	v_lshlrev_b32_e32 v92, 16, v34
	v_and_b32_e32 v93, 0xffff0000, v34
	v_lshlrev_b32_e32 v94, 16, v35
	v_and_b32_e32 v95, 0xffff0000, v35
	v_mul_f32_e32 v8, v93, v93
	v_mul_f32_e32 v9, v95, v95
	v_fmac_f32_e32 v8, v92, v92
	v_fmac_f32_e32 v9, v94, v94
	v_add_f32_e32 v8, v8, v9
	v_add_f32_e32 v17, v17, v8
	ds_bpermute_b32 v18, v10, v17
	s_waitcnt lgkmcnt(0)
	v_add_f32_e32 v17, v17, v18
	ds_bpermute_b32 v18, v11, v17
	s_waitcnt lgkmcnt(0)
; __device__ __forceinline__ void final_norm_pass(const Ctx& C, const bf16* XB, const float* g, float* out) {
;     ...
;         const v2u* xr = (const v2u*)(XB + (size_t)m * D) + C.lane; f32x4 v[8]; float s = 0.f;
; #pragma unroll
;         for (int j = 0; j < 8; ++j) { const v2u w = xr[64 * j]; v[j] = (f32x4){__uint_as_float(w.x << 16), __uint_as_float(w.x & 0xffff0000u), __uint_as_float(w.y << 16), __uint_as_float(w.y & 0xffff0000u)};
;             s += (v[j][0] * v[j][0] + v[j][1] * v[j][1]) + (v[j][2] * v[j][2] + v[j][3] * v[j][3]); }
;         const float rstd = rsqrtf(wave_sum(s) * (1.0f / D) + EPS);
;         const f32x4* gr = (const f32x4*)g + C.lane; f32x4* o = (f32x4*)(out + (size_t)m * D) + C.lane;
; #pragma unroll
;         for (int j = 0; j < 8; ++j) o[64 * j] = v[j] * rstd * gr[64 * j];
	v_add_f32_e32 v17, v17, v18
	ds_bpermute_b32 v18, v12, v17
	s_waitcnt lgkmcnt(0)
	v_add_f32_e32 v17, v17, v18
	ds_bpermute_b32 v18, v13, v17
	s_waitcnt lgkmcnt(0)
	v_add_f32_e32 v17, v17, v18
	ds_bpermute_b32 v18, v14, v17
	s_waitcnt lgkmcnt(0)
	v_add_f32_e32 v17, v17, v18
	ds_bpermute_b32 v18, v15, v17
	s_waitcnt lgkmcnt(0)
	v_add_f32_e32 v17, v17, v18
	v_fmamk_f32 v6, v17, 0x3a000000, v5
	v_rsq_f32_e32 v6, v6
	s_nop 0
	v_pk_mul_f32 v[64:65], v[6:7], v[64:65] op_sel_hi:[0,1]
	v_pk_mul_f32 v[66:67], v[6:7], v[66:67] op_sel_hi:[0,1]
	v_pk_mul_f32 v[96:97], v[128:129], v[64:65]
	v_pk_mul_f32 v[98:99], v[130:131], v[66:67]
	global_store_dwordx4 v2, v[96:99], s[14:15] offset:-4096 sc0 sc1
	v_pk_mul_f32 v[68:69], v[6:7], v[68:69] op_sel_hi:[0,1]
	v_pk_mul_f32 v[70:71], v[6:7], v[70:71] op_sel_hi:[0,1]
	v_pk_mul_f32 v[100:101], v[132:133], v[68:69]
	v_pk_mul_f32 v[102:103], v[134:135], v[70:71]
	global_store_dwordx4 v2, v[100:103], s[14:15] offset:-3072 sc0 sc1
	v_pk_mul_f32 v[72:73], v[6:7], v[72:73] op_sel_hi:[0,1]
	v_pk_mul_f32 v[74:75], v[6:7], v[74:75] op_sel_hi:[0,1]
	v_pk_mul_f32 v[104:105], v[136:137], v[72:73]
	v_pk_mul_f32 v[106:107], v[138:139], v[74:75]
	global_store_dwordx4 v2, v[104:107], s[14:15] offset:-2048 sc0 sc1
	v_pk_mul_f32 v[76:77], v[6:7], v[76:77] op_sel_hi:[0,1]
	v_pk_mul_f32 v[78:79], v[6:7], v[78:79] op_sel_hi:[0,1]
	v_pk_mul_f32 v[108:109], v[140:141], v[76:77]
	v_pk_mul_f32 v[110:111], v[142:143], v[78:79]
	global_store_dwordx4 v2, v[108:111], s[14:15] offset:-1024 sc0 sc1
	v_pk_mul_f32 v[80:81], v[6:7], v[80:81] op_sel_hi:[0,1]
	v_pk_mul_f32 v[82:83], v[6:7], v[82:83] op_sel_hi:[0,1]
	v_pk_mul_f32 v[112:113], v[144:145], v[80:81]
	v_pk_mul_f32 v[114:115], v[146:147], v[82:83]
	global_store_dwordx4 v2, v[112:115], s[14:15] offset:0 sc0 sc1
	v_pk_mul_f32 v[84:85], v[6:7], v[84:85] op_sel_hi:[0,1]
	v_pk_mul_f32 v[86:87], v[6:7], v[86:87] op_sel_hi:[0,1]
	v_pk_mul_f32 v[116:117], v[148:149], v[84:85]
	v_pk_mul_f32 v[118:119], v[150:151], v[86:87]
	global_store_dwordx4 v2, v[116:119], s[14:15] offset:1024 sc0 sc1
	v_pk_mul_f32 v[88:89], v[6:7], v[88:89] op_sel_hi:[0,1]
	v_pk_mul_f32 v[90:91], v[6:7], v[90:91] op_sel_hi:[0,1]
	v_pk_mul_f32 v[120:121], v[152:153], v[88:89]
	v_pk_mul_f32 v[122:123], v[154:155], v[90:91]
	global_store_dwordx4 v2, v[120:123], s[14:15] offset:2048 sc0 sc1
	v_pk_mul_f32 v[92:93], v[6:7], v[92:93] op_sel_hi:[0,1]
	v_pk_mul_f32 v[94:95], v[6:7], v[94:95] op_sel_hi:[0,1]
	v_pk_mul_f32 v[124:125], v[156:157], v[92:93]
	v_pk_mul_f32 v[126:127], v[158:159], v[94:95]
	global_store_dwordx4 v2, v[124:127], s[14:15] offset:3072 sc0 sc1
	s_lshl_b32 s8, s2, 13
	s_add_u32 s14, s4, s8
	s_addc_u32 s15, s5, 0
	s_add_u32 s2, s2, s44
	s_lshl_b32 s8, s2, 12
	s_add_u32 s10, s6, s8
	s_addc_u32 s11, s7, 0
	global_load_dwordx2 v[20:21], v3, s[10:11] offset:-2048
	global_load_dwordx2 v[22:23], v3, s[10:11] offset:-1536
	global_load_dwordx2 v[24:25], v3, s[10:11] offset:-1024
	global_load_dwordx2 v[26:27], v3, s[10:11] offset:-512
	global_load_dwordx2 v[28:29], v3, s[10:11] offset:0
	global_load_dwordx2 v[30:31], v3, s[10:11] offset:512
	global_load_dwordx2 v[32:33], v3, s[10:11] offset:1024
	global_load_dwordx2 v[34:35], v3, s[10:11] offset:1536
	s_waitcnt vmcnt(16)
	v_lshlrev_b32_e32 v64, 16, v36
	v_and_b32_e32 v65, 0xffff0000, v36
	v_lshlrev_b32_e32 v66, 16, v37
	v_and_b32_e32 v67, 0xffff0000, v37
	v_mul_f32_e32 v8, v65, v65
	v_mul_f32_e32 v9, v67, v67
	v_fmac_f32_e32 v8, v64, v64
	v_fmac_f32_e32 v9, v66, v66
	v_add_f32_e32 v17, v8, v9
	v_lshlrev_b32_e32 v68, 16, v38
	v_and_b32_e32 v69, 0xffff0000, v38
	v_lshlrev_b32_e32 v70, 16, v39
	v_and_b32_e32 v71, 0xffff0000, v39
	v_mul_f32_e32 v8, v69, v69
	v_mul_f32_e32 v9, v71, v71
	v_fmac_f32_e32 v8, v68, v68
	v_fmac_f32_e32 v9, v70, v70
	v_add_f32_e32 v8, v8, v9
	v_add_f32_e32 v17, v17, v8
	v_lshlrev_b32_e32 v72, 16, v40
	v_and_b32_e32 v73, 0xffff0000, v40
	v_lshlrev_b32_e32 v74, 16, v41
	v_and_b32_e32 v75, 0xffff0000, v41
	v_mul_f32_e32 v8, v73, v73
	v_mul_f32_e32 v9, v75, v75
	v_fmac_f32_e32 v8, v72, v72
	v_fmac_f32_e32 v9, v74, v74
	v_add_f32_e32 v8, v8, v9
	v_add_f32_e32 v17, v17, v8
	v_lshlrev_b32_e32 v76, 16, v42
	v_and_b32_e32 v77, 0xffff0000, v42
	v_lshlrev_b32_e32 v78, 16, v43
	v_and_b32_e32 v79, 0xffff0000, v43
	v_mul_f32_e32 v8, v77, v77
	v_mul_f32_e32 v9, v79, v79
	v_fmac_f32_e32 v8, v76, v76
	v_fmac_f32_e32 v9, v78, v78
	v_add_f32_e32 v8, v8, v9
	v_add_f32_e32 v17, v17, v8
	v_lshlrev_b32_e32 v80, 16, v44
	v_and_b32_e32 v81, 0xffff0000, v44
	v_lshlrev_b32_e32 v82, 16, v45
	v_and_b32_e32 v83, 0xffff0000, v45
	v_mul_f32_e32 v8, v81, v81
	v_mul_f32_e32 v9, v83, v83
	v_fmac_f32_e32 v8, v80, v80
	v_fmac_f32_e32 v9, v82, v82
	v_add_f32_e32 v8, v8, v9
	v_add_f32_e32 v17, v17, v8
	v_lshlrev_b32_e32 v84, 16, v46
	v_and_b32_e32 v85, 0xffff0000, v46
	v_lshlrev_b32_e32 v86, 16, v47
	v_and_b32_e32 v87, 0xffff0000, v47
	v_mul_f32_e32 v8, v85, v85
	v_mul_f32_e32 v9, v87, v87
	v_fmac_f32_e32 v8, v84, v84
	v_fmac_f32_e32 v9, v86, v86
	v_add_f32_e32 v8, v8, v9
	v_add_f32_e32 v17, v17, v8
	v_lshlrev_b32_e32 v88, 16, v48
	v_and_b32_e32 v89, 0xffff0000, v48
	v_lshlrev_b32_e32 v90, 16, v49
	v_and_b32_e32 v91, 0xffff0000, v49
	v_mul_f32_e32 v8, v89, v89
	v_mul_f32_e32 v9, v91, v91
	v_fmac_f32_e32 v8, v88, v88
	v_fmac_f32_e32 v9, v90, v90
	v_add_f32_e32 v8, v8, v9
	v_add_f32_e32 v17, v17, v8
	v_lshlrev_b32_e32 v92, 16, v50
	v_and_b32_e32 v93, 0xffff0000, v50
	v_lshlrev_b32_e32 v94, 16, v51
	v_and_b32_e32 v95, 0xffff0000, v51
	v_mul_f32_e32 v8, v93, v93
	v_mul_f32_e32 v9, v95, v95
	v_fmac_f32_e32 v8, v92, v92
	v_fmac_f32_e32 v9, v94, v94
	v_add_f32_e32 v8, v8, v9
	v_add_f32_e32 v17, v17, v8
	ds_bpermute_b32 v18, v10, v17
	s_waitcnt lgkmcnt(0)
; __device__ __forceinline__ void final_norm_pass(const Ctx& C, const bf16* XB, const float* g, float* out) {
;     ...
;         const v2u* xr = (const v2u*)(XB + (size_t)m * D) + C.lane; f32x4 v[8]; float s = 0.f;
; #pragma unroll
;         for (int j = 0; j < 8; ++j) { const v2u w = xr[64 * j]; v[j] = (f32x4){__uint_as_float(w.x << 16), __uint_as_float(w.x & 0xffff0000u), __uint_as_float(w.y << 16), __uint_as_float(w.y & 0xffff0000u)};
;             s += (v[j][0] * v[j][0] + v[j][1] * v[j][1]) + (v[j][2] * v[j][2] + v[j][3] * v[j][3]); }
;         const float rstd = rsqrtf(wave_sum(s) * (1.0f / D) + EPS);
;         const f32x4* gr = (const f32x4*)g + C.lane; f32x4* o = (f32x4*)(out + (size_t)m * D) + C.lane;
; #pragma unroll
;         for (int j = 0; j < 8; ++j) o[64 * j] = v[j] * rstd * gr[64 * j];
	v_add_f32_e32 v17, v17, v18
	ds_bpermute_b32 v18, v11, v17
	s_waitcnt lgkmcnt(0)
	v_add_f32_e32 v17, v17, v18
	ds_bpermute_b32 v18, v12, v17
	s_waitcnt lgkmcnt(0)
	v_add_f32_e32 v17, v17, v18
	ds_bpermute_b32 v18, v13, v17
	s_waitcnt lgkmcnt(0)
	v_add_f32_e32 v17, v17, v18
	ds_bpermute_b32 v18, v14, v17
	s_waitcnt lgkmcnt(0)
	v_add_f32_e32 v17, v17, v18
	ds_bpermute_b32 v18, v15, v17
	s_waitcnt lgkmcnt(0)
	v_add_f32_e32 v17, v17, v18
	v_fmamk_f32 v6, v17, 0x3a000000, v5
	v_rsq_f32_e32 v6, v6
	s_nop 0
	v_pk_mul_f32 v[64:65], v[6:7], v[64:65] op_sel_hi:[0,1]
	v_pk_mul_f32 v[66:67], v[6:7], v[66:67] op_sel_hi:[0,1]
	v_pk_mul_f32 v[96:97], v[128:129], v[64:65]
	v_pk_mul_f32 v[98:99], v[130:131], v[66:67]
	global_store_dwordx4 v2, v[96:99], s[14:15] offset:-4096 sc0 sc1
	v_pk_mul_f32 v[68:69], v[6:7], v[68:69] op_sel_hi:[0,1]
	v_pk_mul_f32 v[70:71], v[6:7], v[70:71] op_sel_hi:[0,1]
	v_pk_mul_f32 v[100:101], v[132:133], v[68:69]
	v_pk_mul_f32 v[102:103], v[134:135], v[70:71]
	global_store_dwordx4 v2, v[100:103], s[14:15] offset:-3072 sc0 sc1
	v_pk_mul_f32 v[72:73], v[6:7], v[72:73] op_sel_hi:[0,1]
	v_pk_mul_f32 v[74:75], v[6:7], v[74:75] op_sel_hi:[0,1]
	v_pk_mul_f32 v[104:105], v[136:137], v[72:73]
	v_pk_mul_f32 v[106:107], v[138:139], v[74:75]
	global_store_dwordx4 v2, v[104:107], s[14:15] offset:-2048 sc0 sc1
	v_pk_mul_f32 v[76:77], v[6:7], v[76:77] op_sel_hi:[0,1]
	v_pk_mul_f32 v[78:79], v[6:7], v[78:79] op_sel_hi:[0,1]
	v_pk_mul_f32 v[108:109], v[140:141], v[76:77]
	v_pk_mul_f32 v[110:111], v[142:143], v[78:79]
	global_store_dwordx4 v2, v[108:111], s[14:15] offset:-1024 sc0 sc1
	v_pk_mul_f32 v[80:81], v[6:7], v[80:81] op_sel_hi:[0,1]
	v_pk_mul_f32 v[82:83], v[6:7], v[82:83] op_sel_hi:[0,1]
	v_pk_mul_f32 v[112:113], v[144:145], v[80:81]
	v_pk_mul_f32 v[114:115], v[146:147], v[82:83]
	global_store_dwordx4 v2, v[112:115], s[14:15] offset:0 sc0 sc1
	v_pk_mul_f32 v[84:85], v[6:7], v[84:85] op_sel_hi:[0,1]
	v_pk_mul_f32 v[86:87], v[6:7], v[86:87] op_sel_hi:[0,1]
	v_pk_mul_f32 v[116:117], v[148:149], v[84:85]
	v_pk_mul_f32 v[118:119], v[150:151], v[86:87]
	global_store_dwordx4 v2, v[116:119], s[14:15] offset:1024 sc0 sc1
	v_pk_mul_f32 v[88:89], v[6:7], v[88:89] op_sel_hi:[0,1]
	v_pk_mul_f32 v[90:91], v[6:7], v[90:91] op_sel_hi:[0,1]
	v_pk_mul_f32 v[120:121], v[152:153], v[88:89]
	v_pk_mul_f32 v[122:123], v[154:155], v[90:91]
	global_store_dwordx4 v2, v[120:123], s[14:15] offset:2048 sc0 sc1
	v_pk_mul_f32 v[92:93], v[6:7], v[92:93] op_sel_hi:[0,1]
	v_pk_mul_f32 v[94:95], v[6:7], v[94:95] op_sel_hi:[0,1]
	v_pk_mul_f32 v[124:125], v[156:157], v[92:93]
	v_pk_mul_f32 v[126:127], v[158:159], v[94:95]
	global_store_dwordx4 v2, v[124:127], s[14:15] offset:3072 sc0 sc1
	s_lshl_b32 s8, s2, 13
	s_add_u32 s14, s4, s8
	s_addc_u32 s15, s5, 0
	s_add_u32 s2, s2, s44
	s_lshl_b32 s8, s2, 12
	s_add_u32 s10, s6, s8
	s_addc_u32 s11, s7, 0
	global_load_dwordx2 v[36:37], v3, s[10:11] offset:-2048
	global_load_dwordx2 v[38:39], v3, s[10:11] offset:-1536
	global_load_dwordx2 v[40:41], v3, s[10:11] offset:-1024
	global_load_dwordx2 v[42:43], v3, s[10:11] offset:-512
	global_load_dwordx2 v[44:45], v3, s[10:11] offset:0
	global_load_dwordx2 v[46:47], v3, s[10:11] offset:512
	global_load_dwordx2 v[48:49], v3, s[10:11] offset:1024
	global_load_dwordx2 v[50:51], v3, s[10:11] offset:1536
	s_waitcnt vmcnt(16)
	v_lshlrev_b32_e32 v64, 16, v20
	v_and_b32_e32 v65, 0xffff0000, v20
	v_lshlrev_b32_e32 v66, 16, v21
	v_and_b32_e32 v67, 0xffff0000, v21
	v_mul_f32_e32 v8, v65, v65
	v_mul_f32_e32 v9, v67, v67
	v_fmac_f32_e32 v8, v64, v64
	v_fmac_f32_e32 v9, v66, v66
	v_add_f32_e32 v17, v8, v9
	v_lshlrev_b32_e32 v68, 16, v22
	v_and_b32_e32 v69, 0xffff0000, v22
	v_lshlrev_b32_e32 v70, 16, v23
	v_and_b32_e32 v71, 0xffff0000, v23
	v_mul_f32_e32 v8, v69, v69
	v_mul_f32_e32 v9, v71, v71
	v_fmac_f32_e32 v8, v68, v68
	v_fmac_f32_e32 v9, v70, v70
	v_add_f32_e32 v8, v8, v9
	v_add_f32_e32 v17, v17, v8
	v_lshlrev_b32_e32 v72, 16, v24
	v_and_b32_e32 v73, 0xffff0000, v24
	v_lshlrev_b32_e32 v74, 16, v25
	v_and_b32_e32 v75, 0xffff0000, v25
	v_mul_f32_e32 v8, v73, v73
	v_mul_f32_e32 v9, v75, v75
	v_fmac_f32_e32 v8, v72, v72
	v_fmac_f32_e32 v9, v74, v74
	v_add_f32_e32 v8, v8, v9
	v_add_f32_e32 v17, v17, v8
	v_lshlrev_b32_e32 v76, 16, v26
	v_and_b32_e32 v77, 0xffff0000, v26
	v_lshlrev_b32_e32 v78, 16, v27
	v_and_b32_e32 v79, 0xffff0000, v27
	v_mul_f32_e32 v8, v77, v77
	v_mul_f32_e32 v9, v79, v79
	v_fmac_f32_e32 v8, v76, v76
	v_fmac_f32_e32 v9, v78, v78
	v_add_f32_e32 v8, v8, v9
	v_add_f32_e32 v17, v17, v8
	v_lshlrev_b32_e32 v80, 16, v28
	v_and_b32_e32 v81, 0xffff0000, v28
	v_lshlrev_b32_e32 v82, 16, v29
	v_and_b32_e32 v83, 0xffff0000, v29
	v_mul_f32_e32 v8, v81, v81
	v_mul_f32_e32 v9, v83, v83
	v_fmac_f32_e32 v8, v80, v80
	v_fmac_f32_e32 v9, v82, v82
	v_add_f32_e32 v8, v8, v9
	v_add_f32_e32 v17, v17, v8
	v_lshlrev_b32_e32 v84, 16, v30
	v_and_b32_e32 v85, 0xffff0000, v30
	v_lshlrev_b32_e32 v86, 16, v31
	v_and_b32_e32 v87, 0xffff0000, v31
	v_mul_f32_e32 v8, v85, v85
	v_mul_f32_e32 v9, v87, v87
	v_fmac_f32_e32 v8, v84, v84
	v_fmac_f32_e32 v9, v86, v86
	v_add_f32_e32 v8, v8, v9
	v_add_f32_e32 v17, v17, v8
	v_lshlrev_b32_e32 v88, 16, v32
	v_and_b32_e32 v89, 0xffff0000, v32
	v_lshlrev_b32_e32 v90, 16, v33
	v_and_b32_e32 v91, 0xffff0000, v33
	v_mul_f32_e32 v8, v89, v89
	v_mul_f32_e32 v9, v91, v91
	v_fmac_f32_e32 v8, v88, v88
	v_fmac_f32_e32 v9, v90, v90
	v_add_f32_e32 v8, v8, v9
	v_add_f32_e32 v17, v17, v8
	v_lshlrev_b32_e32 v92, 16, v34
	v_and_b32_e32 v93, 0xffff0000, v34
	v_lshlrev_b32_e32 v94, 16, v35
	v_and_b32_e32 v95, 0xffff0000, v35
	v_mul_f32_e32 v8, v93, v93
	v_mul_f32_e32 v9, v95, v95
	v_fmac_f32_e32 v8, v92, v92
	v_fmac_f32_e32 v9, v94, v94
	v_add_f32_e32 v8, v8, v9
	v_add_f32_e32 v17, v17, v8
	ds_bpermute_b32 v18, v10, v17
	s_waitcnt lgkmcnt(0)
; __device__ __forceinline__ void final_norm_pass(const Ctx& C, const bf16* XB, const float* g, float* out) {
;     ...
;         const v2u* xr = (const v2u*)(XB + (size_t)m * D) + C.lane; f32x4 v[8]; float s = 0.f;
; #pragma unroll
;         for (int j = 0; j < 8; ++j) { const v2u w = xr[64 * j]; v[j] = (f32x4){__uint_as_float(w.x << 16), __uint_as_float(w.x & 0xffff0000u), __uint_as_float(w.y << 16), __uint_as_float(w.y & 0xffff0000u)};
;             s += (v[j][0] * v[j][0] + v[j][1] * v[j][1]) + (v[j][2] * v[j][2] + v[j][3] * v[j][3]); }
;         const float rstd = rsqrtf(wave_sum(s) * (1.0f / D) + EPS);
;         const f32x4* gr = (const f32x4*)g + C.lane; f32x4* o = (f32x4*)(out + (size_t)m * D) + C.lane;
; #pragma unroll
;         for (int j = 0; j < 8; ++j) o[64 * j] = v[j] * rstd * gr[64 * j];
	v_add_f32_e32 v17, v17, v18
	ds_bpermute_b32 v18, v11, v17
	s_waitcnt lgkmcnt(0)
	v_add_f32_e32 v17, v17, v18
	ds_bpermute_b32 v18, v12, v17
	s_waitcnt lgkmcnt(0)
	v_add_f32_e32 v17, v17, v18
	ds_bpermute_b32 v18, v13, v17
	s_waitcnt lgkmcnt(0)
	v_add_f32_e32 v17, v17, v18
	ds_bpermute_b32 v18, v14, v17
	s_waitcnt lgkmcnt(0)
	v_add_f32_e32 v17, v17, v18
	ds_bpermute_b32 v18, v15, v17
	s_waitcnt lgkmcnt(0)
	v_add_f32_e32 v17, v17, v18
	v_fmamk_f32 v6, v17, 0x3a000000, v5
	v_rsq_f32_e32 v6, v6
	s_nop 0
	v_pk_mul_f32 v[64:65], v[6:7], v[64:65] op_sel_hi:[0,1]
	v_pk_mul_f32 v[66:67], v[6:7], v[66:67] op_sel_hi:[0,1]
	v_pk_mul_f32 v[96:97], v[128:129], v[64:65]
	v_pk_mul_f32 v[98:99], v[130:131], v[66:67]
	global_store_dwordx4 v2, v[96:99], s[14:15] offset:-4096 sc0 sc1
	v_pk_mul_f32 v[68:69], v[6:7], v[68:69] op_sel_hi:[0,1]
	v_pk_mul_f32 v[70:71], v[6:7], v[70:71] op_sel_hi:[0,1]
	v_pk_mul_f32 v[100:101], v[132:133], v[68:69]
	v_pk_mul_f32 v[102:103], v[134:135], v[70:71]
	global_store_dwordx4 v2, v[100:103], s[14:15] offset:-3072 sc0 sc1
	v_pk_mul_f32 v[72:73], v[6:7], v[72:73] op_sel_hi:[0,1]
	v_pk_mul_f32 v[74:75], v[6:7], v[74:75] op_sel_hi:[0,1]
	v_pk_mul_f32 v[104:105], v[136:137], v[72:73]
	v_pk_mul_f32 v[106:107], v[138:139], v[74:75]
	global_store_dwordx4 v2, v[104:107], s[14:15] offset:-2048 sc0 sc1
	v_pk_mul_f32 v[76:77], v[6:7], v[76:77] op_sel_hi:[0,1]
	v_pk_mul_f32 v[78:79], v[6:7], v[78:79] op_sel_hi:[0,1]
	v_pk_mul_f32 v[108:109], v[140:141], v[76:77]
	v_pk_mul_f32 v[110:111], v[142:143], v[78:79]
	global_store_dwordx4 v2, v[108:111], s[14:15] offset:-1024 sc0 sc1
	v_pk_mul_f32 v[80:81], v[6:7], v[80:81] op_sel_hi:[0,1]
	v_pk_mul_f32 v[82:83], v[6:7], v[82:83] op_sel_hi:[0,1]
	v_pk_mul_f32 v[112:113], v[144:145], v[80:81]
	v_pk_mul_f32 v[114:115], v[146:147], v[82:83]
	global_store_dwordx4 v2, v[112:115], s[14:15] offset:0 sc0 sc1
	v_pk_mul_f32 v[84:85], v[6:7], v[84:85] op_sel_hi:[0,1]
	v_pk_mul_f32 v[86:87], v[6:7], v[86:87] op_sel_hi:[0,1]
	v_pk_mul_f32 v[116:117], v[148:149], v[84:85]
	v_pk_mul_f32 v[118:119], v[150:151], v[86:87]
	global_store_dwordx4 v2, v[116:119], s[14:15] offset:1024 sc0 sc1
	v_pk_mul_f32 v[88:89], v[6:7], v[88:89] op_sel_hi:[0,1]
	v_pk_mul_f32 v[90:91], v[6:7], v[90:91] op_sel_hi:[0,1]
	v_pk_mul_f32 v[120:121], v[152:153], v[88:89]
	v_pk_mul_f32 v[122:123], v[154:155], v[90:91]
	global_store_dwordx4 v2, v[120:123], s[14:15] offset:2048 sc0 sc1
	v_pk_mul_f32 v[92:93], v[6:7], v[92:93] op_sel_hi:[0,1]
	v_pk_mul_f32 v[94:95], v[6:7], v[94:95] op_sel_hi:[0,1]
	v_pk_mul_f32 v[124:125], v[156:157], v[92:93]
	v_pk_mul_f32 v[126:127], v[158:159], v[94:95]
	global_store_dwordx4 v2, v[124:127], s[14:15] offset:3072 sc0 sc1
	s_lshl_b32 s8, s2, 13
	s_add_u32 s14, s4, s8
	s_addc_u32 s15, s5, 0
	s_add_u32 s2, s2, s44
	s_lshl_b32 s8, s2, 12
	s_add_u32 s10, s6, s8
	s_addc_u32 s11, s7, 0
	global_load_dwordx2 v[20:21], v3, s[10:11] offset:-2048
	global_load_dwordx2 v[22:23], v3, s[10:11] offset:-1536
	global_load_dwordx2 v[24:25], v3, s[10:11] offset:-1024
	global_load_dwordx2 v[26:27], v3, s[10:11] offset:-512
	global_load_dwordx2 v[28:29], v3, s[10:11] offset:0
	global_load_dwordx2 v[30:31], v3, s[10:11] offset:512
	global_load_dwordx2 v[32:33], v3, s[10:11] offset:1024
	global_load_dwordx2 v[34:35], v3, s[10:11] offset:1536
	s_waitcnt vmcnt(16)
	v_lshlrev_b32_e32 v64, 16, v36
	v_and_b32_e32 v65, 0xffff0000, v36
	v_lshlrev_b32_e32 v66, 16, v37
	v_and_b32_e32 v67, 0xffff0000, v37
	v_mul_f32_e32 v8, v65, v65
	v_mul_f32_e32 v9, v67, v67
	v_fmac_f32_e32 v8, v64, v64
	v_fmac_f32_e32 v9, v66, v66
	v_add_f32_e32 v17, v8, v9
	v_lshlrev_b32_e32 v68, 16, v38
	v_and_b32_e32 v69, 0xffff0000, v38
	v_lshlrev_b32_e32 v70, 16, v39
	v_and_b32_e32 v71, 0xffff0000, v39
	v_mul_f32_e32 v8, v69, v69
	v_mul_f32_e32 v9, v71, v71
	v_fmac_f32_e32 v8, v68, v68
	v_fmac_f32_e32 v9, v70, v70
	v_add_f32_e32 v8, v8, v9
	v_add_f32_e32 v17, v17, v8
	v_lshlrev_b32_e32 v72, 16, v40
	v_and_b32_e32 v73, 0xffff0000, v40
	v_lshlrev_b32_e32 v74, 16, v41
	v_and_b32_e32 v75, 0xffff0000, v41
	v_mul_f32_e32 v8, v73, v73
	v_mul_f32_e32 v9, v75, v75
	v_fmac_f32_e32 v8, v72, v72
	v_fmac_f32_e32 v9, v74, v74
	v_add_f32_e32 v8, v8, v9
	v_add_f32_e32 v17, v17, v8
	v_lshlrev_b32_e32 v76, 16, v42
	v_and_b32_e32 v77, 0xffff0000, v42
	v_lshlrev_b32_e32 v78, 16, v43
	v_and_b32_e32 v79, 0xffff0000, v43
	v_mul_f32_e32 v8, v77, v77
	v_mul_f32_e32 v9, v79, v79
	v_fmac_f32_e32 v8, v76, v76
	v_fmac_f32_e32 v9, v78, v78
	v_add_f32_e32 v8, v8, v9
	v_add_f32_e32 v17, v17, v8
	v_lshlrev_b32_e32 v80, 16, v44
	v_and_b32_e32 v81, 0xffff0000, v44
	v_lshlrev_b32_e32 v82, 16, v45
	v_and_b32_e32 v83, 0xffff0000, v45
	v_mul_f32_e32 v8, v81, v81
	v_mul_f32_e32 v9, v83, v83
	v_fmac_f32_e32 v8, v80, v80
	v_fmac_f32_e32 v9, v82, v82
	v_add_f32_e32 v8, v8, v9
	v_add_f32_e32 v17, v17, v8
	v_lshlrev_b32_e32 v84, 16, v46
	v_and_b32_e32 v85, 0xffff0000, v46
	v_lshlrev_b32_e32 v86, 16, v47
	v_and_b32_e32 v87, 0xffff0000, v47
	v_mul_f32_e32 v8, v85, v85
	v_mul_f32_e32 v9, v87, v87
	v_fmac_f32_e32 v8, v84, v84
	v_fmac_f32_e32 v9, v86, v86
	v_add_f32_e32 v8, v8, v9
	v_add_f32_e32 v17, v17, v8
	v_lshlrev_b32_e32 v88, 16, v48
	v_and_b32_e32 v89, 0xffff0000, v48
	v_lshlrev_b32_e32 v90, 16, v49
	v_and_b32_e32 v91, 0xffff0000, v49
	v_mul_f32_e32 v8, v89, v89
	v_mul_f32_e32 v9, v91, v91
	v_fmac_f32_e32 v8, v88, v88
	v_fmac_f32_e32 v9, v90, v90
	v_add_f32_e32 v8, v8, v9
	v_add_f32_e32 v17, v17, v8
	v_lshlrev_b32_e32 v92, 16, v50
	v_and_b32_e32 v93, 0xffff0000, v50
	v_lshlrev_b32_e32 v94, 16, v51
	v_and_b32_e32 v95, 0xffff0000, v51
	v_mul_f32_e32 v8, v93, v93
	v_mul_f32_e32 v9, v95, v95
	v_fmac_f32_e32 v8, v92, v92
	v_fmac_f32_e32 v9, v94, v94
	v_add_f32_e32 v8, v8, v9
	v_add_f32_e32 v17, v17, v8
	ds_bpermute_b32 v18, v10, v17
	s_waitcnt lgkmcnt(0)
; __device__ __forceinline__ void final_norm_pass(const Ctx& C, const bf16* XB, const float* g, float* out) {
;     ...
;         const v2u* xr = (const v2u*)(XB + (size_t)m * D) + C.lane; f32x4 v[8]; float s = 0.f;
; #pragma unroll
;         for (int j = 0; j < 8; ++j) { const v2u w = xr[64 * j]; v[j] = (f32x4){__uint_as_float(w.x << 16), __uint_as_float(w.x & 0xffff0000u), __uint_as_float(w.y << 16), __uint_as_float(w.y & 0xffff0000u)};
;             s += (v[j][0] * v[j][0] + v[j][1] * v[j][1]) + (v[j][2] * v[j][2] + v[j][3] * v[j][3]); }
;         const float rstd = rsqrtf(wave_sum(s) * (1.0f / D) + EPS);
;         const f32x4* gr = (const f32x4*)g + C.lane; f32x4* o = (f32x4*)(out + (size_t)m * D) + C.lane;
; #pragma unroll
;         for (int j = 0; j < 8; ++j) o[64 * j] = v[j] * rstd * gr[64 * j];
	v_add_f32_e32 v17, v17, v18
	ds_bpermute_b32 v18, v11, v17
	s_waitcnt lgkmcnt(0)
	v_add_f32_e32 v17, v17, v18
	ds_bpermute_b32 v18, v12, v17
	s_waitcnt lgkmcnt(0)
	v_add_f32_e32 v17, v17, v18
	ds_bpermute_b32 v18, v13, v17
	s_waitcnt lgkmcnt(0)
	v_add_f32_e32 v17, v17, v18
	ds_bpermute_b32 v18, v14, v17
	s_waitcnt lgkmcnt(0)
	v_add_f32_e32 v17, v17, v18
	ds_bpermute_b32 v18, v15, v17
	s_waitcnt lgkmcnt(0)
	v_add_f32_e32 v17, v17, v18
	v_fmamk_f32 v6, v17, 0x3a000000, v5
	v_rsq_f32_e32 v6, v6
	s_nop 0
	v_pk_mul_f32 v[64:65], v[6:7], v[64:65] op_sel_hi:[0,1]
	v_pk_mul_f32 v[66:67], v[6:7], v[66:67] op_sel_hi:[0,1]
	v_pk_mul_f32 v[96:97], v[128:129], v[64:65]
	v_pk_mul_f32 v[98:99], v[130:131], v[66:67]
	global_store_dwordx4 v2, v[96:99], s[14:15] offset:-4096 sc0 sc1
	v_pk_mul_f32 v[68:69], v[6:7], v[68:69] op_sel_hi:[0,1]
	v_pk_mul_f32 v[70:71], v[6:7], v[70:71] op_sel_hi:[0,1]
	v_pk_mul_f32 v[100:101], v[132:133], v[68:69]
	v_pk_mul_f32 v[102:103], v[134:135], v[70:71]
	global_store_dwordx4 v2, v[100:103], s[14:15] offset:-3072 sc0 sc1
	v_pk_mul_f32 v[72:73], v[6:7], v[72:73] op_sel_hi:[0,1]
	v_pk_mul_f32 v[74:75], v[6:7], v[74:75] op_sel_hi:[0,1]
	v_pk_mul_f32 v[104:105], v[136:137], v[72:73]
	v_pk_mul_f32 v[106:107], v[138:139], v[74:75]
	global_store_dwordx4 v2, v[104:107], s[14:15] offset:-2048 sc0 sc1
	v_pk_mul_f32 v[76:77], v[6:7], v[76:77] op_sel_hi:[0,1]
	v_pk_mul_f32 v[78:79], v[6:7], v[78:79] op_sel_hi:[0,1]
	v_pk_mul_f32 v[108:109], v[140:141], v[76:77]
	v_pk_mul_f32 v[110:111], v[142:143], v[78:79]
	global_store_dwordx4 v2, v[108:111], s[14:15] offset:-1024 sc0 sc1
	v_pk_mul_f32 v[80:81], v[6:7], v[80:81] op_sel_hi:[0,1]
	v_pk_mul_f32 v[82:83], v[6:7], v[82:83] op_sel_hi:[0,1]
	v_pk_mul_f32 v[112:113], v[144:145], v[80:81]
	v_pk_mul_f32 v[114:115], v[146:147], v[82:83]
	global_store_dwordx4 v2, v[112:115], s[14:15] offset:0 sc0 sc1
	v_pk_mul_f32 v[84:85], v[6:7], v[84:85] op_sel_hi:[0,1]
	v_pk_mul_f32 v[86:87], v[6:7], v[86:87] op_sel_hi:[0,1]
	v_pk_mul_f32 v[116:117], v[148:149], v[84:85]
	v_pk_mul_f32 v[118:119], v[150:151], v[86:87]
	global_store_dwordx4 v2, v[116:119], s[14:15] offset:1024 sc0 sc1
	v_pk_mul_f32 v[88:89], v[6:7], v[88:89] op_sel_hi:[0,1]
	v_pk_mul_f32 v[90:91], v[6:7], v[90:91] op_sel_hi:[0,1]
	v_pk_mul_f32 v[120:121], v[152:153], v[88:89]
	v_pk_mul_f32 v[122:123], v[154:155], v[90:91]
	global_store_dwordx4 v2, v[120:123], s[14:15] offset:2048 sc0 sc1
	v_pk_mul_f32 v[92:93], v[6:7], v[92:93] op_sel_hi:[0,1]
	v_pk_mul_f32 v[94:95], v[6:7], v[94:95] op_sel_hi:[0,1]
	v_pk_mul_f32 v[124:125], v[156:157], v[92:93]
	v_pk_mul_f32 v[126:127], v[158:159], v[94:95]
	global_store_dwordx4 v2, v[124:127], s[14:15] offset:3072 sc0 sc1
	s_lshl_b32 s8, s2, 13
	s_add_u32 s14, s4, s8
	s_addc_u32 s15, s5, 0
	s_add_u32 s2, s2, s44
	s_lshl_b32 s8, s2, 12
	s_add_u32 s10, s6, s8
	s_addc_u32 s11, s7, 0
	global_load_dwordx2 v[36:37], v3, s[10:11] offset:-2048
	global_load_dwordx2 v[38:39], v3, s[10:11] offset:-1536
	global_load_dwordx2 v[40:41], v3, s[10:11] offset:-1024
	global_load_dwordx2 v[42:43], v3, s[10:11] offset:-512
	global_load_dwordx2 v[44:45], v3, s[10:11] offset:0
	global_load_dwordx2 v[46:47], v3, s[10:11] offset:512
	global_load_dwordx2 v[48:49], v3, s[10:11] offset:1024
	global_load_dwordx2 v[50:51], v3, s[10:11] offset:1536
	s_waitcnt vmcnt(16)
	v_lshlrev_b32_e32 v64, 16, v20
	v_and_b32_e32 v65, 0xffff0000, v20
	v_lshlrev_b32_e32 v66, 16, v21
	v_and_b32_e32 v67, 0xffff0000, v21
	v_mul_f32_e32 v8, v65, v65
	v_mul_f32_e32 v9, v67, v67
	v_fmac_f32_e32 v8, v64, v64
	v_fmac_f32_e32 v9, v66, v66
	v_add_f32_e32 v17, v8, v9
	v_lshlrev_b32_e32 v68, 16, v22
	v_and_b32_e32 v69, 0xffff0000, v22
	v_lshlrev_b32_e32 v70, 16, v23
	v_and_b32_e32 v71, 0xffff0000, v23
	v_mul_f32_e32 v8, v69, v69
	v_mul_f32_e32 v9, v71, v71
	v_fmac_f32_e32 v8, v68, v68
	v_fmac_f32_e32 v9, v70, v70
	v_add_f32_e32 v8, v8, v9
	v_add_f32_e32 v17, v17, v8
	v_lshlrev_b32_e32 v72, 16, v24
	v_and_b32_e32 v73, 0xffff0000, v24
	v_lshlrev_b32_e32 v74, 16, v25
	v_and_b32_e32 v75, 0xffff0000, v25
	v_mul_f32_e32 v8, v73, v73
	v_mul_f32_e32 v9, v75, v75
	v_fmac_f32_e32 v8, v72, v72
	v_fmac_f32_e32 v9, v74, v74
	v_add_f32_e32 v8, v8, v9
	v_add_f32_e32 v17, v17, v8
	v_lshlrev_b32_e32 v76, 16, v26
	v_and_b32_e32 v77, 0xffff0000, v26
	v_lshlrev_b32_e32 v78, 16, v27
	v_and_b32_e32 v79, 0xffff0000, v27
	v_mul_f32_e32 v8, v77, v77
	v_mul_f32_e32 v9, v79, v79
	v_fmac_f32_e32 v8, v76, v76
	v_fmac_f32_e32 v9, v78, v78
	v_add_f32_e32 v8, v8, v9
	v_add_f32_e32 v17, v17, v8
	v_lshlrev_b32_e32 v80, 16, v28
	v_and_b32_e32 v81, 0xffff0000, v28
	v_lshlrev_b32_e32 v82, 16, v29
	v_and_b32_e32 v83, 0xffff0000, v29
	v_mul_f32_e32 v8, v81, v81
	v_mul_f32_e32 v9, v83, v83
	v_fmac_f32_e32 v8, v80, v80
	v_fmac_f32_e32 v9, v82, v82
	v_add_f32_e32 v8, v8, v9
	v_add_f32_e32 v17, v17, v8
	v_lshlrev_b32_e32 v84, 16, v30
	v_and_b32_e32 v85, 0xffff0000, v30
	v_lshlrev_b32_e32 v86, 16, v31
	v_and_b32_e32 v87, 0xffff0000, v31
	v_mul_f32_e32 v8, v85, v85
	v_mul_f32_e32 v9, v87, v87
	v_fmac_f32_e32 v8, v84, v84
	v_fmac_f32_e32 v9, v86, v86
	v_add_f32_e32 v8, v8, v9
	v_add_f32_e32 v17, v17, v8
	v_lshlrev_b32_e32 v88, 16, v32
	v_and_b32_e32 v89, 0xffff0000, v32
	v_lshlrev_b32_e32 v90, 16, v33
	v_and_b32_e32 v91, 0xffff0000, v33
	v_mul_f32_e32 v8, v89, v89
	v_mul_f32_e32 v9, v91, v91
	v_fmac_f32_e32 v8, v88, v88
	v_fmac_f32_e32 v9, v90, v90
	v_add_f32_e32 v8, v8, v9
	v_add_f32_e32 v17, v17, v8
	v_lshlrev_b32_e32 v92, 16, v34
	v_and_b32_e32 v93, 0xffff0000, v34
	v_lshlrev_b32_e32 v94, 16, v35
	v_and_b32_e32 v95, 0xffff0000, v35
	v_mul_f32_e32 v8, v93, v93
	v_mul_f32_e32 v9, v95, v95
	v_fmac_f32_e32 v8, v92, v92
	v_fmac_f32_e32 v9, v94, v94
	v_add_f32_e32 v8, v8, v9
	v_add_f32_e32 v17, v17, v8
	ds_bpermute_b32 v18, v10, v17
	s_waitcnt lgkmcnt(0)
; __device__ __forceinline__ void final_norm_pass(const Ctx& C, const bf16* XB, const float* g, float* out) {
;     ...
;         const v2u* xr = (const v2u*)(XB + (size_t)m * D) + C.lane; f32x4 v[8]; float s = 0.f;
; #pragma unroll
;         for (int j = 0; j < 8; ++j) { const v2u w = xr[64 * j]; v[j] = (f32x4){__uint_as_float(w.x << 16), __uint_as_float(w.x & 0xffff0000u), __uint_as_float(w.y << 16), __uint_as_float(w.y & 0xffff0000u)};
;             s += (v[j][0] * v[j][0] + v[j][1] * v[j][1]) + (v[j][2] * v[j][2] + v[j][3] * v[j][3]); }
;         const float rstd = rsqrtf(wave_sum(s) * (1.0f / D) + EPS);
;         const f32x4* gr = (const f32x4*)g + C.lane; f32x4* o = (f32x4*)(out + (size_t)m * D) + C.lane;
; #pragma unroll
;         for (int j = 0; j < 8; ++j) o[64 * j] = v[j] * rstd * gr[64 * j];
	v_add_f32_e32 v17, v17, v18
	ds_bpermute_b32 v18, v11, v17
	s_waitcnt lgkmcnt(0)
	v_add_f32_e32 v17, v17, v18
	ds_bpermute_b32 v18, v12, v17
	s_waitcnt lgkmcnt(0)
	v_add_f32_e32 v17, v17, v18
	ds_bpermute_b32 v18, v13, v17
	s_waitcnt lgkmcnt(0)
	v_add_f32_e32 v17, v17, v18
	ds_bpermute_b32 v18, v14, v17
	s_waitcnt lgkmcnt(0)
	v_add_f32_e32 v17, v17, v18
	ds_bpermute_b32 v18, v15, v17
	s_waitcnt lgkmcnt(0)
	v_add_f32_e32 v17, v17, v18
	v_fmamk_f32 v6, v17, 0x3a000000, v5
	v_rsq_f32_e32 v6, v6
	s_nop 0
	v_pk_mul_f32 v[64:65], v[6:7], v[64:65] op_sel_hi:[0,1]
	v_pk_mul_f32 v[66:67], v[6:7], v[66:67] op_sel_hi:[0,1]
	v_pk_mul_f32 v[96:97], v[128:129], v[64:65]
	v_pk_mul_f32 v[98:99], v[130:131], v[66:67]
	global_store_dwordx4 v2, v[96:99], s[14:15] offset:-4096 sc0 sc1
	v_pk_mul_f32 v[68:69], v[6:7], v[68:69] op_sel_hi:[0,1]
	v_pk_mul_f32 v[70:71], v[6:7], v[70:71] op_sel_hi:[0,1]
	v_pk_mul_f32 v[100:101], v[132:133], v[68:69]
	v_pk_mul_f32 v[102:103], v[134:135], v[70:71]
	global_store_dwordx4 v2, v[100:103], s[14:15] offset:-3072 sc0 sc1
	v_pk_mul_f32 v[72:73], v[6:7], v[72:73] op_sel_hi:[0,1]
	v_pk_mul_f32 v[74:75], v[6:7], v[74:75] op_sel_hi:[0,1]
	v_pk_mul_f32 v[104:105], v[136:137], v[72:73]
	v_pk_mul_f32 v[106:107], v[138:139], v[74:75]
	global_store_dwordx4 v2, v[104:107], s[14:15] offset:-2048 sc0 sc1
	v_pk_mul_f32 v[76:77], v[6:7], v[76:77] op_sel_hi:[0,1]
	v_pk_mul_f32 v[78:79], v[6:7], v[78:79] op_sel_hi:[0,1]
	v_pk_mul_f32 v[108:109], v[140:141], v[76:77]
	v_pk_mul_f32 v[110:111], v[142:143], v[78:79]
	global_store_dwordx4 v2, v[108:111], s[14:15] offset:-1024 sc0 sc1
	v_pk_mul_f32 v[80:81], v[6:7], v[80:81] op_sel_hi:[0,1]
	v_pk_mul_f32 v[82:83], v[6:7], v[82:83] op_sel_hi:[0,1]
	v_pk_mul_f32 v[112:113], v[144:145], v[80:81]
	v_pk_mul_f32 v[114:115], v[146:147], v[82:83]
	global_store_dwordx4 v2, v[112:115], s[14:15] offset:0 sc0 sc1
	v_pk_mul_f32 v[84:85], v[6:7], v[84:85] op_sel_hi:[0,1]
	v_pk_mul_f32 v[86:87], v[6:7], v[86:87] op_sel_hi:[0,1]
	v_pk_mul_f32 v[116:117], v[148:149], v[84:85]
	v_pk_mul_f32 v[118:119], v[150:151], v[86:87]
	global_store_dwordx4 v2, v[116:119], s[14:15] offset:1024 sc0 sc1
	v_pk_mul_f32 v[88:89], v[6:7], v[88:89] op_sel_hi:[0,1]
	v_pk_mul_f32 v[90:91], v[6:7], v[90:91] op_sel_hi:[0,1]
	v_pk_mul_f32 v[120:121], v[152:153], v[88:89]
	v_pk_mul_f32 v[122:123], v[154:155], v[90:91]
	global_store_dwordx4 v2, v[120:123], s[14:15] offset:2048 sc0 sc1
	v_pk_mul_f32 v[92:93], v[6:7], v[92:93] op_sel_hi:[0,1]
	v_pk_mul_f32 v[94:95], v[6:7], v[94:95] op_sel_hi:[0,1]
	v_pk_mul_f32 v[124:125], v[156:157], v[92:93]
	v_pk_mul_f32 v[126:127], v[158:159], v[94:95]
	global_store_dwordx4 v2, v[124:127], s[14:15] offset:3072 sc0 sc1
	s_lshl_b32 s8, s2, 13
	s_add_u32 s14, s4, s8
	s_addc_u32 s15, s5, 0
	s_waitcnt vmcnt(8)
; __device__ __forceinline__ void final_norm_pass(const Ctx& C, const bf16* XB, const float* g, float* out) {
;     ...
;         const v2u* xr = (const v2u*)(XB + (size_t)m * D) + C.lane; f32x4 v[8]; float s = 0.f;
; #pragma unroll
;         for (int j = 0; j < 8; ++j) { const v2u w = xr[64 * j]; v[j] = (f32x4){__uint_as_float(w.x << 16), __uint_as_float(w.x & 0xffff0000u), __uint_as_float(w.y << 16), __uint_as_float(w.y & 0xffff0000u)};
;             s += (v[j][0] * v[j][0] + v[j][1] * v[j][1]) + (v[j][2] * v[j][2] + v[j][3] * v[j][3]); }
;         const float rstd = rsqrtf(wave_sum(s) * (1.0f / D) + EPS);
;         const f32x4* gr = (const f32x4*)g + C.lane; f32x4* o = (f32x4*)(out + (size_t)m * D) + C.lane;
; #pragma unroll
;         for (int j = 0; j < 8; ++j) o[64 * j] = v[j] * rstd * gr[64 * j];
	v_lshlrev_b32_e32 v64, 16, v36
	v_and_b32_e32 v65, 0xffff0000, v36
	v_lshlrev_b32_e32 v66, 16, v37
	v_and_b32_e32 v67, 0xffff0000, v37
	v_mul_f32_e32 v8, v65, v65
	v_mul_f32_e32 v9, v67, v67
	v_fmac_f32_e32 v8, v64, v64
	v_fmac_f32_e32 v9, v66, v66
	v_add_f32_e32 v17, v8, v9
	v_lshlrev_b32_e32 v68, 16, v38
	v_and_b32_e32 v69, 0xffff0000, v38
	v_lshlrev_b32_e32 v70, 16, v39
	v_and_b32_e32 v71, 0xffff0000, v39
	v_mul_f32_e32 v8, v69, v69
	v_mul_f32_e32 v9, v71, v71
	v_fmac_f32_e32 v8, v68, v68
	v_fmac_f32_e32 v9, v70, v70
	v_add_f32_e32 v8, v8, v9
	v_add_f32_e32 v17, v17, v8
	v_lshlrev_b32_e32 v72, 16, v40
	v_and_b32_e32 v73, 0xffff0000, v40
	v_lshlrev_b32_e32 v74, 16, v41
	v_and_b32_e32 v75, 0xffff0000, v41
	v_mul_f32_e32 v8, v73, v73
	v_mul_f32_e32 v9, v75, v75
	v_fmac_f32_e32 v8, v72, v72
	v_fmac_f32_e32 v9, v74, v74
	v_add_f32_e32 v8, v8, v9
	v_add_f32_e32 v17, v17, v8
	v_lshlrev_b32_e32 v76, 16, v42
	v_and_b32_e32 v77, 0xffff0000, v42
	v_lshlrev_b32_e32 v78, 16, v43
	v_and_b32_e32 v79, 0xffff0000, v43
	v_mul_f32_e32 v8, v77, v77
	v_mul_f32_e32 v9, v79, v79
	v_fmac_f32_e32 v8, v76, v76
	v_fmac_f32_e32 v9, v78, v78
	v_add_f32_e32 v8, v8, v9
	v_add_f32_e32 v17, v17, v8
	v_lshlrev_b32_e32 v80, 16, v44
	v_and_b32_e32 v81, 0xffff0000, v44
	v_lshlrev_b32_e32 v82, 16, v45
	v_and_b32_e32 v83, 0xffff0000, v45
	v_mul_f32_e32 v8, v81, v81
	v_mul_f32_e32 v9, v83, v83
	v_fmac_f32_e32 v8, v80, v80
	v_fmac_f32_e32 v9, v82, v82
	v_add_f32_e32 v8, v8, v9
	v_add_f32_e32 v17, v17, v8
	v_lshlrev_b32_e32 v84, 16, v46
	v_and_b32_e32 v85, 0xffff0000, v46
	v_lshlrev_b32_e32 v86, 16, v47
	v_and_b32_e32 v87, 0xffff0000, v47
	v_mul_f32_e32 v8, v85, v85
	v_mul_f32_e32 v9, v87, v87
	v_fmac_f32_e32 v8, v84, v84
	v_fmac_f32_e32 v9, v86, v86
	v_add_f32_e32 v8, v8, v9
	v_add_f32_e32 v17, v17, v8
	v_lshlrev_b32_e32 v88, 16, v48
	v_and_b32_e32 v89, 0xffff0000, v48
	v_lshlrev_b32_e32 v90, 16, v49
	v_and_b32_e32 v91, 0xffff0000, v49
	v_mul_f32_e32 v8, v89, v89
	v_mul_f32_e32 v9, v91, v91
	v_fmac_f32_e32 v8, v88, v88
	v_fmac_f32_e32 v9, v90, v90
	v_add_f32_e32 v8, v8, v9
	v_add_f32_e32 v17, v17, v8
	v_lshlrev_b32_e32 v92, 16, v50
	v_and_b32_e32 v93, 0xffff0000, v50
	v_lshlrev_b32_e32 v94, 16, v51
	v_and_b32_e32 v95, 0xffff0000, v51
	v_mul_f32_e32 v8, v93, v93
	v_mul_f32_e32 v9, v95, v95
	v_fmac_f32_e32 v8, v92, v92
	v_fmac_f32_e32 v9, v94, v94
	v_add_f32_e32 v8, v8, v9
	v_add_f32_e32 v17, v17, v8
	ds_bpermute_b32 v18, v10, v17
	s_waitcnt lgkmcnt(0)
	v_add_f32_e32 v17, v17, v18
	ds_bpermute_b32 v18, v11, v17
	s_waitcnt lgkmcnt(0)
	v_add_f32_e32 v17, v17, v18
	ds_bpermute_b32 v18, v12, v17
	s_waitcnt lgkmcnt(0)
	v_add_f32_e32 v17, v17, v18
	ds_bpermute_b32 v18, v13, v17
	s_waitcnt lgkmcnt(0)
	v_add_f32_e32 v17, v17, v18
	ds_bpermute_b32 v18, v14, v17
	s_waitcnt lgkmcnt(0)
	v_add_f32_e32 v17, v17, v18
	ds_bpermute_b32 v18, v15, v17
	s_waitcnt lgkmcnt(0)
	v_add_f32_e32 v17, v17, v18
	v_fmamk_f32 v6, v17, 0x3a000000, v5
	v_rsq_f32_e32 v6, v6
	s_nop 0
	v_pk_mul_f32 v[64:65], v[6:7], v[64:65] op_sel_hi:[0,1]
	v_pk_mul_f32 v[66:67], v[6:7], v[66:67] op_sel_hi:[0,1]
	v_pk_mul_f32 v[96:97], v[128:129], v[64:65]
	v_pk_mul_f32 v[98:99], v[130:131], v[66:67]
	global_store_dwordx4 v2, v[96:99], s[14:15] offset:-4096 sc0 sc1
	v_pk_mul_f32 v[68:69], v[6:7], v[68:69] op_sel_hi:[0,1]
	v_pk_mul_f32 v[70:71], v[6:7], v[70:71] op_sel_hi:[0,1]
	v_pk_mul_f32 v[100:101], v[132:133], v[68:69]
	v_pk_mul_f32 v[102:103], v[134:135], v[70:71]
	global_store_dwordx4 v2, v[100:103], s[14:15] offset:-3072 sc0 sc1
	v_pk_mul_f32 v[72:73], v[6:7], v[72:73] op_sel_hi:[0,1]
	v_pk_mul_f32 v[74:75], v[6:7], v[74:75] op_sel_hi:[0,1]
	v_pk_mul_f32 v[104:105], v[136:137], v[72:73]
	v_pk_mul_f32 v[106:107], v[138:139], v[74:75]
	global_store_dwordx4 v2, v[104:107], s[14:15] offset:-2048 sc0 sc1
	v_pk_mul_f32 v[76:77], v[6:7], v[76:77] op_sel_hi:[0,1]
	v_pk_mul_f32 v[78:79], v[6:7], v[78:79] op_sel_hi:[0,1]
	v_pk_mul_f32 v[108:109], v[140:141], v[76:77]
	v_pk_mul_f32 v[110:111], v[142:143], v[78:79]
	global_store_dwordx4 v2, v[108:111], s[14:15] offset:-1024 sc0 sc1
	v_pk_mul_f32 v[80:81], v[6:7], v[80:81] op_sel_hi:[0,1]
	v_pk_mul_f32 v[82:83], v[6:7], v[82:83] op_sel_hi:[0,1]
	v_pk_mul_f32 v[112:113], v[144:145], v[80:81]
	v_pk_mul_f32 v[114:115], v[146:147], v[82:83]
	global_store_dwordx4 v2, v[112:115], s[14:15] offset:0 sc0 sc1
	v_pk_mul_f32 v[84:85], v[6:7], v[84:85] op_sel_hi:[0,1]
	v_pk_mul_f32 v[86:87], v[6:7], v[86:87] op_sel_hi:[0,1]
	v_pk_mul_f32 v[116:117], v[148:149], v[84:85]
	v_pk_mul_f32 v[118:119], v[150:151], v[86:87]
	global_store_dwordx4 v2, v[116:119], s[14:15] offset:1024 sc0 sc1
	v_pk_mul_f32 v[88:89], v[6:7], v[88:89] op_sel_hi:[0,1]
	v_pk_mul_f32 v[90:91], v[6:7], v[90:91] op_sel_hi:[0,1]
	v_pk_mul_f32 v[120:121], v[152:153], v[88:89]
	v_pk_mul_f32 v[122:123], v[154:155], v[90:91]
	global_store_dwordx4 v2, v[120:123], s[14:15] offset:2048 sc0 sc1
	v_pk_mul_f32 v[92:93], v[6:7], v[92:93] op_sel_hi:[0,1]
	v_pk_mul_f32 v[94:95], v[6:7], v[94:95] op_sel_hi:[0,1]
	v_pk_mul_f32 v[124:125], v[156:157], v[92:93]
	v_pk_mul_f32 v[126:127], v[158:159], v[94:95]
	global_store_dwordx4 v2, v[124:127], s[14:15] offset:3072 sc0 sc1
